# tail units: sample split-K units of down GEMMs (ks=10) run by WGs idle in last round of gate/up GEMMs via flag sync + phase re-entry; reversed tile order; no consumer L2 invalidate
# speedup vs baseline: 1.0593x; 1.0054x over previous
_Z10fwd_kernel4Args:
	s_mov_b32 s98, 0
	s_mov_b64 s[100:101], s[0:1]
	v_readfirstlane_b32 s99, v0
	s_nop 3
	v_writelane_b32 v255, s99, 63
.Lp_reentry:
	s_load_dwordx2 s[94:95], s[0:1], 0xd0
	s_load_dwordx4 s[4:7], s[0:1], 0xc0
	s_load_dword s16, s[0:1], 0xe8
	s_load_dwordx4 s[12:15], s[0:1], 0xd8
	s_load_dwordx2 s[34:35], s[0:1], 0xf0
	v_and_b32_e32 v175, 0x3ff, v0
	v_cmp_gt_u32_e32 vcc, 64, v175
	s_waitcnt lgkmcnt(0)
	s_cmp_lg_u32 s98, 1
	s_cbranch_scc1 .Lm_n1
	s_mov_b32 s12, 4
	s_mov_b32 s13, 5
.Lm_n1:
	s_cmp_lg_u32 s98, 2
	s_cbranch_scc1 .Lm_n2
	s_mov_b32 s12, 3
.Lm_n2:
	s_cmp_lg_u32 s98, 3
	s_cbranch_scc1 .Lm_n3
	s_mov_b32 s12, 12
	s_mov_b32 s13, 13
.Lm_n3:
	s_cmp_lg_u32 s98, 4
	s_cbranch_scc1 .Lm_n4
	s_mov_b32 s12, 11
.Lm_n4:
	v_writelane_b32 v254, s4, 0
	s_nop 1
	v_writelane_b32 v254, s5, 1
	v_writelane_b32 v254, s6, 2
	v_writelane_b32 v254, s7, 3
	s_add_u32 s6, s0, 0xf0
	s_addc_u32 s7, s1, 0
	s_cmp_eq_u32 s98, 0
	s_cbranch_scc1 .Lp_first1
	s_mov_b64 vcc, 0
.Lp_first1:
	s_and_saveexec_b64 s[4:5], vcc
	v_lshl_add_u32 v1, v175, 2, 0
	v_add_u32_e32 v1, 0x20000, v1
	v_mov_b32_e32 v2, 0
	ds_write_b32 v1, v2
	s_or_b64 exec, exec, s[4:5]
	s_load_dword s75, s[0:1], 0xf8
	s_waitcnt lgkmcnt(0)
	s_barrier
	s_add_u32 s76, s94, 0x1000
	s_getreg_b32 s3, hwreg(HW_REG_XCC_ID, 0, 4)
	s_addc_u32 s77, s95, 0
	s_and_b32 s33, s3, 15
	v_cmp_eq_u32_e64 s[8:9], 0, v175
	s_mov_b64 s[4:5], exec
	s_nop 0
	v_writelane_b32 v254, s8, 4
	s_nop 1
	v_writelane_b32 v254, s9, 5
	s_and_b64 s[8:9], s[4:5], s[8:9]
	s_mov_b64 exec, s[8:9]
	s_cbranch_execz .LBB0_5
	s_mov_b64 s[8:9], exec
	v_mbcnt_lo_u32_b32 v1, s8, 0
	v_mbcnt_hi_u32_b32 v1, s9, v1
	v_cmp_eq_u32_e32 vcc, 0, v1
	s_and_b64 s[10:11], exec, vcc
	s_mov_b64 exec, s[10:11]
	s_cbranch_execz .LBB0_5
	s_lshl_b32 s3, s33, 8
	s_bcnt1_i32_b64 s8, s[8:9]
	v_mov_b32_e32 v1, s3
	v_mov_b32_e32 v2, s8
	s_cmp_lg_u32 s98, 0
	s_cbranch_scc1 .Lp_skip_post
	global_atomic_add v1, v2, s[76:77] offset:1024
.Lp_skip_post:
.LBB0_5:
	s_or_b64 exec, exec, s[4:5]
	s_cmp_gt_i32 s12, -1
	v_writelane_b32 v254, s12, 6
	s_nop 1
	v_writelane_b32 v254, s13, 7
	v_writelane_b32 v254, s14, 8
	v_writelane_b32 v254, s15, 9
	s_cbranch_scc1 .LBB0_17
	v_lshrrev_b32_e32 v1, 20, v0
	v_lshrrev_b32_e32 v0, 10, v0
	v_or_b32_e32 v0, v0, v1
	s_movk_i32 s3, 0x3ff
	v_and_or_b32 v0, v0, s3, v175
	v_cmp_eq_u32_e32 vcc, 0, v0
	s_barrier
	s_and_saveexec_b64 s[4:5], vcc
	s_cbranch_execz .LBB0_16
	buffer_wbl2 sc1
	s_waitcnt vmcnt(0)
	s_load_dwordx2 s[6:7], s[6:7], 0x58
	v_mov_b32_e32 v2, 0
	s_mov_b64 s[8:9], exec
	v_mbcnt_lo_u32_b32 v1, s8, 0
	v_mbcnt_hi_u32_b32 v1, s9, v1
	s_waitcnt lgkmcnt(0)
	global_load_dword v0, v2, s[6:7] offset:40
	v_cmp_eq_u32_e32 vcc, 0, v1
	s_and_saveexec_b64 s[10:11], vcc
	s_cbranch_execz .LBB0_9
	s_bcnt1_i32_b64 s3, s[8:9]
	v_mov_b32_e32 v3, s3
	global_atomic_add v3, v2, v3, s[6:7] offset:32 sc0

.LBB0_310:
	s_cmp_lt_i32 s84, 4
	s_cselect_b64 s[4:5], -1, 0
	s_add_u32 s18, s94, 0x6a00000
	s_addc_u32 s19, s95, 0
	s_and_b64 s[4:5], s[4:5], s[0:1]
	s_andn2_b64 vcc, exec, s[4:5]
	s_cbranch_vccnz .LBB0_335
	s_cmp_eq_u32 s98, 2
	s_cbranch_scc1 .LBB0_335
	s_cmpk_gt_i32 s2, 0x5ab
	v_readfirstlane_b32 s8, v175
	s_cbranch_scc1 .LBB0_335
	s_ashr_i32 s3, s2, 31
	s_lshr_b32 s0, s3, 29
	s_add_i32 s7, s2, s0
	s_and_b32 s0, s7, -8
	s_sub_i32 s9, s2, s0
	s_cmp_gt_i32 s9, 3
	s_cbranch_scc0 .LBB0_314
	s_mul_i32 s0, s9, 0xb5
	s_add_i32 s6, s0, 4
	s_cbranch_execz .LBB0_315
	s_branch .LBB0_316

.LBB0_316:
	s_waitcnt vmcnt(3)
	v_lshrrev_b32_e32 v2, 1, v175
	s_waitcnt vmcnt(1)
	v_and_b32_e32 v11, 24, v2
	v_lshrrev_b32_e32 v2, 5, v175
	v_and_b32_e32 v2, 4, v2
	v_bfe_u32 v3, v175, 2, 2
	s_ashr_i32 s0, s7, 3
	v_lshlrev_b32_e32 v0, 4, v175
	v_and_b32_e32 v1, 32, v175
	v_bfe_u32 v10, v175, 2, 4
	v_or3_b32 v2, v2, v3, v11
	v_lshrrev_b32_e32 v3, 3, v175
	s_movk_i32 s7, 0x70
	v_bitop3_b32 v8, v0, v1, 48 bitop3:0x6c
	v_and_b32_e32 v9, 64, v175
	v_and_or_b32 v4, v3, s7, v10
	s_movk_i32 s7, 0x60
	s_waitcnt vmcnt(0)
	v_add_u32_e32 v12, 0x2000, v0
	v_or_b32_e32 v1, v8, v9
	v_and_or_b32 v3, v3, s7, v2
	v_lshrrev_b32_e32 v0, 7, v12
	s_movk_i32 s7, 0xf0
	s_add_i32 s0, s6, s0
	s_sub_i32 s0, 0x5ab, s0
	v_lshl_or_b32 v130, v3, 11, v1
	v_and_or_b32 v3, v0, s7, v10
	s_movk_i32 s7, 0xe0
	s_mul_hi_i32 s6, s0, 0x2e8ba2e9
	v_and_or_b32 v0, v0, s7, v2
	s_lshr_b32 s7, s6, 31
	s_ashr_i32 s6, s6, 4
	s_add_i32 s6, s6, s7
	s_lshl_b32 s11, s6, 2
	s_sub_i32 s7, 0x42, s11
	s_mulk_i32 s6, 0x58
	s_min_u32 s12, s7, 4
	s_sub_i32 s13, s0, s6
	v_lshl_or_b32 v128, v4, 11, v1
	v_lshl_or_b32 v132, v3, 11, v1
	v_lshl_or_b32 v134, v0, 11, v1
	s_sext_i32_i8 s0, s13
	v_cvt_f32_ubyte0_e32 v1, s12
	v_cvt_f32_i32_e32 v0, s0
	v_rcp_iflag_f32_e32 v2, v1
	s_lshr_b32 s9, s8, 6
	s_ashr_i32 s0, s0, 30
	s_lshr_b32 s1, s8, 8
	v_mul_f32_e32 v2, v0, v2
	v_trunc_f32_e32 v2, v2
	v_fma_f32 v0, -v2, v1, v0
	v_cvt_i32_f32_e32 v2, v2
	s_lshl_b32 s10, s9, 10
	s_or_b32 s0, s0, 1
	v_cmp_ge_f32_e64 s[6:7], |v0|, v1
	s_and_b64 s[6:7], s[6:7], exec
	s_cselect_b32 s0, s0, 0
	v_readfirstlane_b32 s6, v2
	s_add_i32 s0, s6, s0
	s_mul_i32 s6, s0, s12
	s_sub_i32 s6, s13, s6
	s_sext_i32_i8 s6, s6
	s_waitcnt lgkmcnt(0)
	s_add_i32 s58, s11, s6
	s_ashr_i32 s59, s58, 31
	s_bfe_i64 s[12:13], s[0:1], 0x80000
	s_lshl_b64 s[6:7], s[58:59], 19
	s_lshl_b64 s[12:13], s[12:13], 19
	s_add_u32 s70, s90, s12
	s_addc_u32 s71, s91, s13
	s_add_i32 s11, s10, 0
	s_add_i32 m0, s11, 0x10000
	v_mov_b32_e32 v131, 0
	global_load_lds_dwordx4 v130, s[70:71]
	s_add_i32 m0, s11, 0x12000
	s_add_u32 s12, s70, 0x40000
	global_load_lds_dwordx4 v134, s[70:71]
	s_addc_u32 s13, s71, 0
	s_add_i32 m0, s11, 0x14000
	v_mov_b32_e32 v135, v131
	global_load_lds_dwordx4 v130, s[12:13]
	s_add_i32 m0, s11, 0x16000
	s_add_u32 s6, s24, s6
	global_load_lds_dwordx4 v134, s[12:13]
	s_addc_u32 s7, s25, s7
	s_add_i32 s12, s11, 0x2000
	s_mov_b32 m0, s11
	s_add_u32 s16, s6, 0x40000
	global_load_lds_dwordx4 v128, s[6:7]
	s_mov_b32 m0, s12
	s_addc_u32 s17, s7, 0
	s_add_i32 s13, s11, 0x4000
	global_load_lds_dwordx4 v132, s[6:7]
	s_mov_b32 m0, s13
	s_add_i32 s14, s11, 0x6000
	global_load_lds_dwordx4 v128, s[16:17]
	s_mov_b32 m0, s14
	v_mov_b32_e32 v129, v131
	global_load_lds_dwordx4 v132, s[16:17]
	v_mov_b32_e32 v133, v131
	s_cmp_eq_u32 s1, 1
	s_mov_b32 s15, 0
	v_lshl_add_u64 v[6:7], s[70:71], 0, v[130:131]
	v_lshl_add_u64 v[4:5], s[70:71], 0, v[134:135]
	v_lshl_add_u64 v[0:1], s[6:7], 0, v[128:129]
	s_cselect_b64 s[22:23], -1, 0
	s_cmp_lg_u32 s1, 1
	v_lshl_add_u64 v[2:3], s[6:7], 0, v[132:133]
	s_cbranch_scc1 .LBB0_318
	s_barrier

.LBB0_326:
	s_ashr_i32 s8, s38, 3
	s_add_i32 s8, s40, s8
	s_sub_i32 s8, 0x5ab, s8
	s_mul_hi_i32 s9, s8, 0x2e8ba2e9
	s_lshr_b32 s38, s9, 31
	s_ashr_i32 s9, s9, 4
	s_add_i32 s9, s9, s38
	s_lshl_b32 s38, s9, 2
	s_sub_i32 s39, 0x42, s38
	s_min_i32 s39, s39, 4
	s_abs_i32 s40, s39
	v_cvt_f32_u32_e32 v0, s40
	s_sub_i32 s42, 0, s40
	s_mulk_i32 s9, 0x58
	s_sub_i32 s8, s8, s9
	v_rcp_iflag_f32_e32 v0, v0
	s_abs_i32 s9, s8
	s_xor_b32 s41, s8, s39
	s_ashr_i32 s41, s41, 31
	v_mul_f32_e32 v0, 0x4f7ffffe, v0
	v_cvt_u32_f32_e32 v0, v0
	s_nop 0
	v_readfirstlane_b32 s43, v0
	s_mul_i32 s42, s42, s43
	s_mul_hi_u32 s42, s43, s42
	s_add_i32 s43, s43, s42
	s_mul_hi_u32 s42, s9, s43
	s_mul_i32 s43, s42, s40
	s_sub_i32 s9, s9, s43
	s_add_i32 s44, s42, 1
	s_sub_i32 s43, s9, s40
	s_cmp_ge_u32 s9, s40
	s_cselect_b32 s42, s44, s42
	s_cselect_b32 s9, s43, s9
	s_add_i32 s43, s42, 1
	s_cmp_ge_u32 s9, s40
	s_cselect_b32 s9, s43, s42
	s_xor_b32 s9, s9, s41
	s_sub_i32 s48, s9, s41
	s_mul_i32 s9, s48, s39
	s_sub_i32 s8, s8, s9
	s_add_i32 s50, s38, s8

.LBB0_331:
	v_mul_f32_e32 v157, 0xbfb8aa3b, v124
	v_exp_f32_e32 v157, v157
	v_mul_f32_e32 v160, 0xbfb8aa3b, v125
	v_exp_f32_e32 v160, v160
	v_lshl_or_b32 v148, s37, 7, v152
	v_add_f32_e32 v157, 1.0, v157
	v_rcp_f32_e32 v157, v157
	v_add_f32_e32 v160, 1.0, v160
	v_rcp_f32_e32 v160, v160
	v_lshl_add_u32 v156, s58, 8, v150
	v_mul_f32_e32 v124, v124, v157
	v_mul_f32_e32 v116, v116, v124
	v_mul_f32_e32 v124, v125, v160
	v_mul_f32_e32 v125, 0xbfb8aa3b, v126
	v_exp_f32_e32 v125, v125
	v_mul_f32_e32 v157, 0xbfb8aa3b, v127
	v_exp_f32_e32 v157, v157
	v_mul_f32_e32 v117, v117, v124
	v_add_f32_e32 v124, 1.0, v125
	v_rcp_f32_e32 v124, v124
	v_add_f32_e32 v125, 1.0, v157
	v_rcp_f32_e32 v125, v125
	v_cvt_pk_bf16_f32 v116, v116, v117
	v_mul_f32_e32 v117, v126, v124
	v_mul_f32_e32 v124, 0xbfb8aa3b, v120
	v_exp_f32_e32 v124, v124
	v_mul_f32_e32 v117, v118, v117
	v_mul_f32_e32 v118, v127, v125
	v_mul_f32_e32 v125, 0xbfb8aa3b, v121
	v_exp_f32_e32 v125, v125
	v_mul_f32_e32 v118, v119, v118
	v_add_f32_e32 v119, 1.0, v124
	v_rcp_f32_e32 v119, v119
	v_add_f32_e32 v124, 1.0, v125
	v_rcp_f32_e32 v124, v124
	v_cvt_pk_bf16_f32 v117, v117, v118
	v_mul_f32_e32 v118, v120, v119
	v_mul_f32_e32 v119, 0xbfb8aa3b, v122
	v_exp_f32_e32 v119, v119
	v_mul_f32_e32 v120, 0xbfb8aa3b, v123
	v_exp_f32_e32 v120, v120
	v_mul_f32_e32 v112, v112, v118
	v_mul_f32_e32 v118, v121, v124
	v_mul_f32_e32 v113, v113, v118
	v_add_f32_e32 v118, 1.0, v119
	v_rcp_f32_e32 v119, v118
	v_add_f32_e32 v118, 1.0, v120
	v_rcp_f32_e32 v120, v118
	v_cvt_pk_bf16_f32 v118, v112, v113
	v_mul_f32_e32 v112, v122, v119
	v_mul_f32_e32 v112, v114, v112
	v_mul_f32_e32 v113, v123, v120
	v_mul_f32_e32 v113, v115, v113
	v_cvt_pk_bf16_f32 v119, v112, v113
	v_mul_f32_e32 v113, 0xbfb8aa3b, v108
	v_exp_f32_e32 v114, v113
	v_mul_f32_e32 v113, 0xbfb8aa3b, v109
	v_exp_f32_e32 v115, v113
	v_ashrrev_i32_e32 v149, 31, v148
	v_add_f32_e32 v114, 1.0, v114
	v_rcp_f32_e32 v114, v114
	v_add_f32_e32 v115, 1.0, v115
	v_rcp_f32_e32 v115, v115
	v_mov_b64_e32 v[146:147], s[18:19]
	v_mul_f32_e32 v108, v108, v114
	v_mul_f32_e32 v100, v100, v108
	v_mul_f32_e32 v108, v109, v115
	v_mul_f32_e32 v109, 0xbfb8aa3b, v110
	v_exp_f32_e32 v109, v109
	v_mul_f32_e32 v114, 0xbfb8aa3b, v111
	v_exp_f32_e32 v114, v114
	v_mul_f32_e32 v101, v101, v108
	v_add_f32_e32 v108, 1.0, v109
	v_rcp_f32_e32 v108, v108
	v_mad_i64_i32 v[158:159], s[6:7], v156, s36, v[146:147]
	v_lshlrev_b64 v[148:149], 1, v[148:149]
	v_lshl_add_u64 v[158:159], v[158:159], 0, v[148:149]
	v_add_f32_e32 v109, 1.0, v114
	global_store_dwordx4 v[158:159], v[116:119], off
	v_rcp_f32_e32 v109, v109
	v_cvt_pk_bf16_f32 v100, v100, v101
	v_mul_f32_e32 v101, v110, v108
	v_mul_f32_e32 v108, 0xbfb8aa3b, v104
	v_exp_f32_e32 v108, v108
	v_mul_f32_e32 v101, v102, v101
	v_mul_f32_e32 v102, v111, v109
	v_mul_f32_e32 v109, 0xbfb8aa3b, v105
	v_exp_f32_e32 v109, v109
	v_mul_f32_e32 v102, v103, v102
	v_add_f32_e32 v103, 1.0, v108
	v_rcp_f32_e32 v103, v103
	v_add_f32_e32 v108, 1.0, v109
	v_rcp_f32_e32 v108, v108
	v_cvt_pk_bf16_f32 v101, v101, v102
	v_mul_f32_e32 v102, v104, v103
	v_mul_f32_e32 v103, 0xbfb8aa3b, v106
	v_exp_f32_e32 v103, v103
	v_mul_f32_e32 v104, 0xbfb8aa3b, v107
	v_exp_f32_e32 v104, v104
	v_mul_f32_e32 v96, v96, v102
	v_mul_f32_e32 v102, v105, v108
	v_mul_f32_e32 v97, v97, v102
	v_add_f32_e32 v102, 1.0, v103
	v_rcp_f32_e32 v103, v102
	v_add_f32_e32 v102, 1.0, v104
	v_rcp_f32_e32 v104, v102
	v_cvt_pk_bf16_f32 v102, v96, v97
	v_mul_f32_e32 v96, v106, v103
	v_mul_f32_e32 v96, v98, v96
	v_mul_f32_e32 v97, v107, v104
	v_mul_f32_e32 v97, v99, v97
	v_cvt_pk_bf16_f32 v103, v96, v97
	v_mul_f32_e32 v97, 0xbfb8aa3b, v92
	v_exp_f32_e32 v98, v97
	v_mul_f32_e32 v97, 0xbfb8aa3b, v93
	v_exp_f32_e32 v99, v97
	v_or_b32_e32 v112, 16, v156
	v_add_f32_e32 v98, 1.0, v98
	v_rcp_f32_e32 v98, v98
	v_add_f32_e32 v99, 1.0, v99
	v_rcp_f32_e32 v99, v99
	v_mad_i64_i32 v[112:113], s[6:7], v112, s36, v[146:147]
	v_mul_f32_e32 v92, v92, v98
	v_mul_f32_e32 v84, v84, v92
	v_mul_f32_e32 v92, v93, v99
	v_mul_f32_e32 v93, 0xbfb8aa3b, v94
	v_exp_f32_e32 v93, v93
	v_mul_f32_e32 v98, 0xbfb8aa3b, v95
	v_exp_f32_e32 v98, v98
	v_mul_f32_e32 v85, v85, v92
	v_add_f32_e32 v92, 1.0, v93
	v_rcp_f32_e32 v92, v92
	v_lshl_add_u64 v[112:113], v[112:113], 0, v[148:149]
	v_add_f32_e32 v93, 1.0, v98
	global_store_dwordx4 v[112:113], v[100:103], off
	v_rcp_f32_e32 v93, v93
	v_cvt_pk_bf16_f32 v84, v84, v85
	v_mul_f32_e32 v85, v94, v92
	v_mul_f32_e32 v92, 0xbfb8aa3b, v88
	v_exp_f32_e32 v92, v92
	v_mul_f32_e32 v85, v86, v85
	v_mul_f32_e32 v86, v95, v93
	v_mul_f32_e32 v93, 0xbfb8aa3b, v89
	v_exp_f32_e32 v93, v93
	v_mul_f32_e32 v86, v87, v86
	v_add_f32_e32 v87, 1.0, v92
	v_rcp_f32_e32 v87, v87
	v_add_f32_e32 v92, 1.0, v93
	v_rcp_f32_e32 v92, v92
	v_cvt_pk_bf16_f32 v85, v85, v86
	v_mul_f32_e32 v86, v88, v87
	v_mul_f32_e32 v87, 0xbfb8aa3b, v90
	v_exp_f32_e32 v87, v87
	v_mul_f32_e32 v88, 0xbfb8aa3b, v91
	v_exp_f32_e32 v88, v88
	v_mul_f32_e32 v80, v80, v86
	v_mul_f32_e32 v86, v89, v92
	v_mul_f32_e32 v81, v81, v86
	v_add_f32_e32 v86, 1.0, v87
	v_rcp_f32_e32 v87, v86
	v_add_f32_e32 v86, 1.0, v88
	v_rcp_f32_e32 v88, v86
	v_cvt_pk_bf16_f32 v86, v80, v81
	v_mul_f32_e32 v80, v90, v87
	v_mul_f32_e32 v80, v82, v80
	v_mul_f32_e32 v81, v91, v88
	v_mul_f32_e32 v81, v83, v81
	v_cvt_pk_bf16_f32 v87, v80, v81
	v_mul_f32_e32 v81, 0xbfb8aa3b, v76
	v_exp_f32_e32 v82, v81
	v_mul_f32_e32 v81, 0xbfb8aa3b, v77
	v_exp_f32_e32 v83, v81
	v_or_b32_e32 v96, 32, v156
	v_add_f32_e32 v82, 1.0, v82
	v_rcp_f32_e32 v82, v82
	v_add_f32_e32 v83, 1.0, v83
	v_rcp_f32_e32 v83, v83
	v_mad_i64_i32 v[96:97], s[6:7], v96, s36, v[146:147]
	v_mul_f32_e32 v76, v76, v82
	v_mul_f32_e32 v68, v68, v76
	v_mul_f32_e32 v76, v77, v83
	v_mul_f32_e32 v77, 0xbfb8aa3b, v78
	v_exp_f32_e32 v77, v77
	v_mul_f32_e32 v82, 0xbfb8aa3b, v79
	v_exp_f32_e32 v82, v82
	v_mul_f32_e32 v69, v69, v76
	v_add_f32_e32 v76, 1.0, v77
	v_rcp_f32_e32 v76, v76
	v_lshl_add_u64 v[96:97], v[96:97], 0, v[148:149]
	v_add_f32_e32 v77, 1.0, v82
	global_store_dwordx4 v[96:97], v[84:87], off
	v_rcp_f32_e32 v77, v77
	v_cvt_pk_bf16_f32 v68, v68, v69
	v_mul_f32_e32 v69, v78, v76
	v_mul_f32_e32 v76, 0xbfb8aa3b, v72
	v_exp_f32_e32 v76, v76
	v_mul_f32_e32 v69, v70, v69
	v_mul_f32_e32 v70, v79, v77
	v_mul_f32_e32 v77, 0xbfb8aa3b, v73
	v_exp_f32_e32 v77, v77
	v_mul_f32_e32 v70, v71, v70
	v_add_f32_e32 v71, 1.0, v76
	v_rcp_f32_e32 v71, v71
	v_add_f32_e32 v76, 1.0, v77
	v_rcp_f32_e32 v76, v76
	v_cvt_pk_bf16_f32 v69, v69, v70
	v_mul_f32_e32 v70, v72, v71
	v_mul_f32_e32 v71, 0xbfb8aa3b, v74
	v_exp_f32_e32 v71, v71
	v_mul_f32_e32 v72, 0xbfb8aa3b, v75
	v_exp_f32_e32 v72, v72
	v_mul_f32_e32 v64, v64, v70
	v_mul_f32_e32 v70, v73, v76
	v_mul_f32_e32 v65, v65, v70
	v_add_f32_e32 v70, 1.0, v71
	v_rcp_f32_e32 v71, v70
	v_add_f32_e32 v70, 1.0, v72
	v_rcp_f32_e32 v72, v70
	v_cvt_pk_bf16_f32 v70, v64, v65
	v_mul_f32_e32 v64, v74, v71
	v_mul_f32_e32 v64, v66, v64
	v_mul_f32_e32 v65, v75, v72
	v_mul_f32_e32 v65, v67, v65
	v_cvt_pk_bf16_f32 v71, v64, v65
	v_mul_f32_e32 v65, 0xbfb8aa3b, v60
	v_exp_f32_e32 v66, v65
	v_mul_f32_e32 v65, 0xbfb8aa3b, v61
	v_exp_f32_e32 v67, v65
	v_or_b32_e32 v80, 48, v156
	v_add_f32_e32 v66, 1.0, v66
	v_rcp_f32_e32 v66, v66
	v_add_f32_e32 v67, 1.0, v67
	v_rcp_f32_e32 v67, v67
	v_mad_i64_i32 v[80:81], s[6:7], v80, s36, v[146:147]
	v_mul_f32_e32 v60, v60, v66
	v_mul_f32_e32 v52, v52, v60
	v_mul_f32_e32 v60, v61, v67
	v_mul_f32_e32 v61, 0xbfb8aa3b, v62
	v_exp_f32_e32 v61, v61
	v_mul_f32_e32 v66, 0xbfb8aa3b, v63
	v_exp_f32_e32 v66, v66
	v_mul_f32_e32 v53, v53, v60
	v_add_f32_e32 v60, 1.0, v61
	v_rcp_f32_e32 v60, v60
	v_lshl_add_u64 v[80:81], v[80:81], 0, v[148:149]
	v_add_f32_e32 v61, 1.0, v66
	global_store_dwordx4 v[80:81], v[68:71], off
	v_rcp_f32_e32 v61, v61
	v_cvt_pk_bf16_f32 v52, v52, v53
	v_mul_f32_e32 v53, v62, v60
	v_mul_f32_e32 v60, 0xbfb8aa3b, v56
	v_exp_f32_e32 v60, v60
	v_mul_f32_e32 v53, v54, v53
	v_mul_f32_e32 v54, v63, v61
	v_mul_f32_e32 v61, 0xbfb8aa3b, v57
	v_exp_f32_e32 v61, v61
	v_mul_f32_e32 v54, v55, v54
	v_add_f32_e32 v55, 1.0, v60
	v_rcp_f32_e32 v55, v55
	v_add_f32_e32 v60, 1.0, v61
	v_rcp_f32_e32 v60, v60
	v_cvt_pk_bf16_f32 v53, v53, v54
	v_mul_f32_e32 v54, v56, v55
	v_mul_f32_e32 v55, 0xbfb8aa3b, v58
	v_exp_f32_e32 v55, v55
	v_mul_f32_e32 v56, 0xbfb8aa3b, v59
	v_exp_f32_e32 v56, v56
	v_mul_f32_e32 v48, v48, v54
	v_mul_f32_e32 v54, v57, v60
	v_mul_f32_e32 v49, v49, v54
	v_add_f32_e32 v54, 1.0, v55
	v_rcp_f32_e32 v55, v54
	v_add_f32_e32 v54, 1.0, v56
	v_rcp_f32_e32 v56, v54
	v_cvt_pk_bf16_f32 v54, v48, v49
	v_mul_f32_e32 v48, v58, v55
	v_mul_f32_e32 v48, v50, v48
	v_mul_f32_e32 v49, v59, v56
	v_mul_f32_e32 v49, v51, v49
	v_cvt_pk_bf16_f32 v55, v48, v49
	v_mul_f32_e32 v49, 0xbfb8aa3b, v44
	v_exp_f32_e32 v50, v49
	v_mul_f32_e32 v49, 0xbfb8aa3b, v45
	v_exp_f32_e32 v51, v49
	v_add_u32_e32 v64, 0x80, v156
	v_add_f32_e32 v50, 1.0, v50
	v_rcp_f32_e32 v50, v50
	v_add_f32_e32 v51, 1.0, v51
	v_rcp_f32_e32 v51, v51
	v_mad_i64_i32 v[64:65], s[6:7], v64, s36, v[146:147]
	v_mul_f32_e32 v44, v44, v50
	v_mul_f32_e32 v36, v36, v44
	v_mul_f32_e32 v44, v45, v51
	v_mul_f32_e32 v45, 0xbfb8aa3b, v46
	v_exp_f32_e32 v45, v45
	v_mul_f32_e32 v50, 0xbfb8aa3b, v47
	v_exp_f32_e32 v50, v50
	v_mul_f32_e32 v37, v37, v44
	v_add_f32_e32 v44, 1.0, v45
	v_rcp_f32_e32 v44, v44
	v_lshl_add_u64 v[64:65], v[64:65], 0, v[148:149]
	v_add_f32_e32 v45, 1.0, v50
	global_store_dwordx4 v[64:65], v[52:55], off
	v_rcp_f32_e32 v45, v45
	v_cvt_pk_bf16_f32 v36, v36, v37
	v_mul_f32_e32 v37, v46, v44
	v_mul_f32_e32 v44, 0xbfb8aa3b, v40
	v_exp_f32_e32 v44, v44
	v_mul_f32_e32 v37, v38, v37
	v_mul_f32_e32 v38, v47, v45
	v_mul_f32_e32 v45, 0xbfb8aa3b, v41
	v_exp_f32_e32 v45, v45
	v_mul_f32_e32 v38, v39, v38
	v_add_f32_e32 v39, 1.0, v44
	v_rcp_f32_e32 v39, v39
	v_add_f32_e32 v44, 1.0, v45
	v_rcp_f32_e32 v44, v44
	v_cvt_pk_bf16_f32 v37, v37, v38
	v_mul_f32_e32 v38, v40, v39
	v_mul_f32_e32 v39, 0xbfb8aa3b, v42
	v_exp_f32_e32 v39, v39
	v_mul_f32_e32 v40, 0xbfb8aa3b, v43
	v_exp_f32_e32 v40, v40
	v_mul_f32_e32 v32, v32, v38
	v_mul_f32_e32 v38, v41, v44
	v_mul_f32_e32 v33, v33, v38
	v_add_f32_e32 v38, 1.0, v39
	v_rcp_f32_e32 v39, v38
	v_add_f32_e32 v38, 1.0, v40
	v_rcp_f32_e32 v40, v38
	v_cvt_pk_bf16_f32 v38, v32, v33
	v_mul_f32_e32 v32, v42, v39
	v_mul_f32_e32 v32, v34, v32
	v_mul_f32_e32 v33, v43, v40
	v_mul_f32_e32 v33, v35, v33
	v_cvt_pk_bf16_f32 v39, v32, v33
	v_mul_f32_e32 v33, 0xbfb8aa3b, v28
	v_exp_f32_e32 v34, v33
	v_mul_f32_e32 v33, 0xbfb8aa3b, v29
	v_exp_f32_e32 v35, v33
	v_add_u32_e32 v48, 0x90, v156
	v_add_f32_e32 v34, 1.0, v34
	v_rcp_f32_e32 v34, v34
	v_add_f32_e32 v35, 1.0, v35
	v_rcp_f32_e32 v35, v35
	v_mad_i64_i32 v[48:49], s[6:7], v48, s36, v[146:147]
	v_mul_f32_e32 v28, v28, v34
	v_mul_f32_e32 v20, v20, v28
	v_mul_f32_e32 v28, v29, v35
	v_mul_f32_e32 v29, 0xbfb8aa3b, v30
	v_exp_f32_e32 v29, v29
	v_mul_f32_e32 v34, 0xbfb8aa3b, v31
	v_exp_f32_e32 v34, v34
	v_mul_f32_e32 v21, v21, v28
	v_add_f32_e32 v28, 1.0, v29
	v_rcp_f32_e32 v28, v28
	v_lshl_add_u64 v[48:49], v[48:49], 0, v[148:149]
	v_add_f32_e32 v29, 1.0, v34
	global_store_dwordx4 v[48:49], v[36:39], off
	v_rcp_f32_e32 v29, v29
	v_cvt_pk_bf16_f32 v20, v20, v21
	v_mul_f32_e32 v21, v30, v28
	v_mul_f32_e32 v28, 0xbfb8aa3b, v24
	v_exp_f32_e32 v28, v28
	v_mul_f32_e32 v21, v22, v21
	v_mul_f32_e32 v22, v31, v29
	v_mul_f32_e32 v29, 0xbfb8aa3b, v25
	v_exp_f32_e32 v29, v29
	v_mul_f32_e32 v22, v23, v22
	v_add_f32_e32 v23, 1.0, v28
	v_rcp_f32_e32 v23, v23
	v_add_f32_e32 v28, 1.0, v29
	v_rcp_f32_e32 v28, v28
	v_cvt_pk_bf16_f32 v21, v21, v22
	v_mul_f32_e32 v22, v24, v23
	v_mul_f32_e32 v23, 0xbfb8aa3b, v26
	v_exp_f32_e32 v23, v23
	v_mul_f32_e32 v24, 0xbfb8aa3b, v27
	v_exp_f32_e32 v24, v24
	v_mul_f32_e32 v16, v16, v22
	v_mul_f32_e32 v22, v25, v28
	v_mul_f32_e32 v17, v17, v22
	v_add_f32_e32 v22, 1.0, v23
	v_rcp_f32_e32 v23, v22
	v_add_f32_e32 v22, 1.0, v24
	v_rcp_f32_e32 v24, v22
	v_cvt_pk_bf16_f32 v22, v16, v17
	v_mul_f32_e32 v16, v26, v23
	v_mul_f32_e32 v16, v18, v16
	v_mul_f32_e32 v17, v27, v24
	v_mul_f32_e32 v17, v19, v17
	v_cvt_pk_bf16_f32 v23, v16, v17
	v_mul_f32_e32 v17, 0xbfb8aa3b, v12
	v_exp_f32_e32 v18, v17
	v_mul_f32_e32 v17, 0xbfb8aa3b, v13
	v_exp_f32_e32 v19, v17
	v_add_u32_e32 v32, 0xa0, v156
	v_add_f32_e32 v18, 1.0, v18
	v_rcp_f32_e32 v18, v18
	v_add_f32_e32 v19, 1.0, v19
	v_rcp_f32_e32 v19, v19
	v_mad_i64_i32 v[32:33], s[6:7], v32, s36, v[146:147]
	v_mul_f32_e32 v12, v12, v18
	v_mul_f32_e32 v4, v4, v12
	v_mul_f32_e32 v12, v13, v19
	v_mul_f32_e32 v13, 0xbfb8aa3b, v14
	v_exp_f32_e32 v13, v13
	v_mul_f32_e32 v18, 0xbfb8aa3b, v15
	v_exp_f32_e32 v18, v18
	v_mul_f32_e32 v5, v5, v12
	v_add_f32_e32 v12, 1.0, v13
	v_rcp_f32_e32 v12, v12
	v_lshl_add_u64 v[32:33], v[32:33], 0, v[148:149]
	v_add_f32_e32 v13, 1.0, v18
	global_store_dwordx4 v[32:33], v[20:23], off
	v_rcp_f32_e32 v13, v13
	v_cvt_pk_bf16_f32 v4, v4, v5
	v_mul_f32_e32 v5, v14, v12
	v_mul_f32_e32 v12, 0xbfb8aa3b, v8
	v_exp_f32_e32 v12, v12
	v_mul_f32_e32 v5, v6, v5
	v_mul_f32_e32 v6, v15, v13
	v_mul_f32_e32 v13, 0xbfb8aa3b, v9
	v_exp_f32_e32 v13, v13
	v_mul_f32_e32 v6, v7, v6
	v_add_f32_e32 v7, 1.0, v12
	v_rcp_f32_e32 v7, v7
	v_add_f32_e32 v12, 1.0, v13
	v_rcp_f32_e32 v12, v12
	v_cvt_pk_bf16_f32 v5, v5, v6
	v_mul_f32_e32 v6, v8, v7
	v_mul_f32_e32 v7, 0xbfb8aa3b, v10
	v_exp_f32_e32 v7, v7
	v_mul_f32_e32 v8, 0xbfb8aa3b, v11
	v_exp_f32_e32 v8, v8
	v_mul_f32_e32 v0, v0, v6
	v_mul_f32_e32 v6, v9, v12
	v_mul_f32_e32 v1, v1, v6
	v_add_f32_e32 v6, 1.0, v7
	v_rcp_f32_e32 v7, v6
	v_add_f32_e32 v6, 1.0, v8
	v_rcp_f32_e32 v8, v6
	v_add_u32_e32 v16, 0xb0, v156
	v_mad_i64_i32 v[16:17], s[6:7], v16, s36, v[146:147]
	v_lshl_add_u64 v[16:17], v[16:17], 0, v[148:149]
	v_cvt_pk_bf16_f32 v6, v0, v1
	v_mul_f32_e32 v0, v10, v7
	v_mul_f32_e32 v1, v11, v8
	s_andn2_b64 vcc, exec, s[0:1]
	s_mov_b64 s[0:1], -1
	v_mul_f32_e32 v0, v2, v0
	v_mul_f32_e32 v1, v3, v1
	v_cvt_pk_bf16_f32 v7, v0, v1
	global_store_dwordx4 v[16:17], v[4:7], off
	s_cmp_lt_i32 s58, 64
	s_cbranch_scc1 .Lsg3_skip
	s_waitcnt vmcnt(0)
	s_mov_b64 exec, 1
	s_lshl_b32 s99, s2, 2
	v_mov_b32_e32 v0, 0x4c00
	v_add_u32_e32 v0, s99, v0
	v_mov_b32_e32 v1, 1
	global_atomic_add v2, v0, v1, s[94:95] sc0
	s_waitcnt vmcnt(0)
	v_readfirstlane_b32 s99, v2
	s_nop 1
	s_and_b32 s99, s99, 7
	s_cmp_lg_u32 s99, 7
	s_cbranch_scc1 .Lsg3_done
	buffer_wbl2 sc1
	s_waitcnt vmcnt(0)
	v_mov_b32_e32 v0, 0x4a00
	global_atomic_add v0, v1, s[94:95]
.Lsg3_done:
	s_mov_b64 exec, -1
.Lsg3_skip:
	s_cbranch_vccnz .LBB0_320
	s_andn2_b64 vcc, exec, s[22:23]
	s_cbranch_vccnz .LBB0_319
	s_barrier
	s_branch .LBB0_319

.LBB0_335:
	s_cmp_gt_i32 s85, 4
	s_cselect_b64 s[0:1], -1, 0
	s_and_b64 s[4:5], s[4:5], s[0:1]
	s_andn2_b64 vcc, exec, s[4:5]
	s_cbranch_vccnz .LBB0_387
	s_cmp_lg_u32 s98, 0
	s_cbranch_scc1 .Ltg3_no
	s_cmp_lt_u32 s2, 172
	s_cbranch_scc1 .Ltg3_no
	s_cmp_gt_u32 s2, 251
	s_cbranch_scc1 .Ltg3_no
	s_mov_b32 s98, 1
	s_mov_b64 exec, -1
	s_mov_b64 s[0:1], s[100:101]
	v_readlane_b32 s99, v255, 63
	v_mbcnt_lo_u32_b32 v0, -1, 0
	v_mbcnt_hi_u32_b32 v0, -1, v0
	s_nop 1
	v_add_u32_e32 v0, s99, v0
	s_branch .Lp_reentry
.Ltg3_no:
	s_waitcnt vmcnt(0)
	s_waitcnt vmcnt(0) lgkmcnt(0)
	s_barrier
	s_mov_b64 s[4:5], exec
	v_readlane_b32 s6, v254, 4
	v_readlane_b32 s7, v254, 5
	s_and_b64 s[6:7], s[4:5], s[6:7]
	s_mov_b64 exec, s[6:7]
	s_cbranch_execz .LBB0_386
	s_add_i32 s3, 0, 0x20020
	v_mov_b32_e32 v0, s3
	s_waitcnt vmcnt(0) expcnt(0) lgkmcnt(0)
	ds_read_b32 v2, v0
	s_add_i32 s3, 0, 0x20024
	v_mov_b32_e32 v0, s3
	ds_read_b32 v0, v0
	s_waitcnt lgkmcnt(1)
	v_cmp_ne_u32_e32 vcc, 0, v2
	s_cbranch_vccnz .LBB0_352
	s_add_u32 s6, s94, 0x1200
	s_addc_u32 s7, s95, 0
	s_add_u32 s8, s94, 0x1400
	s_addc_u32 s9, s95, 0
	s_add_u32 s10, s94, 0x1500
	s_addc_u32 s11, s95, 0
	s_add_u32 s12, s94, 0x1600
	s_addc_u32 s13, s95, 0
	s_add_u32 s14, s94, 0x1700
	s_addc_u32 s15, s95, 0
	s_add_u32 s16, s94, 0x1800
	s_addc_u32 s17, s95, 0
	s_add_u32 s20, s94, 0x1900
	s_addc_u32 s21, s95, 0
	s_add_u32 s22, s94, 0x1a00
	s_addc_u32 s23, s95, 0
	s_add_u32 s26, s94, 0x1b00
	s_addc_u32 s27, s95, 0
	s_add_u32 s28, s94, 0x1c00
	s_addc_u32 s29, s95, 0
	s_add_u32 s30, s94, 0x1d00
	s_addc_u32 s31, s95, 0
	s_add_u32 s36, s94, 0x1e00
	s_addc_u32 s37, s95, 0
	s_add_u32 s38, s94, 0x1f00
	s_addc_u32 s39, s95, 0
	s_add_u32 s40, s94, 0x2000
	s_addc_u32 s41, s95, 0
	s_add_u32 s42, s94, 0x2100
	s_addc_u32 s43, s95, 0
	s_add_u32 s44, s94, 0x2200
	s_addc_u32 s45, s95, 0
	s_mul_i32 s3, s35, s75
	s_add_u32 s46, s94, 0x2300
	s_mul_i32 s3, s3, s34
	s_addc_u32 s47, s95, 0
	s_mov_b32 s54, 1
	v_mov_b32_e32 v16, 0
	s_branch .LBB0_340

.LBB0_387:
	s_cmp_lt_i32 s84, 5
	s_cselect_b64 s[4:5], -1, 0
	s_add_u32 s26, s94, 0xe600000
	s_addc_u32 s27, s95, 0
	s_add_u32 s22, s94, 0xc500000
	s_addc_u32 s23, s95, 0
	s_and_b64 s[0:1], s[4:5], s[0:1]
	s_andn2_b64 vcc, exec, s[0:1]
	s_cbranch_vccnz .LBB0_439
	s_cmpk_lg_i32 s34, 0x100
	s_cselect_b64 s[4:5], -1, 0
	s_cmpk_gt_i32 s2, 0x57
	s_cselect_b64 s[6:7], -1, 0
	s_mov_b64 s[30:31], -1
	v_readfirstlane_b32 s28, v175
	s_and_b64 vcc, exec, s[30:31]
	s_cbranch_vccz .LBB0_391
	s_cmpk_gt_i32 s2, 0xff
	s_mov_b64 s[8:9], 0
	s_cbranch_scc0 .LBB0_392
	s_add_u32 s4, s2, 0xffffff00
	s_addc_u32 s5, 0, -1
	s_waitcnt vmcnt(0)
	v_mov_b64_e32 v[0:1], 0x58
	v_cmp_lt_u64_e64 s[6:7], s[4:5], v[0:1]
	s_mov_b64 s[10:11], 0
	s_andn2_b64 vcc, exec, s[10:11]
	s_cbranch_vccnz .LBB0_398
	s_branch .LBB0_393

.LBB0_403:
	s_cmp_lg_u32 s98, 1
	s_cbranch_scc1 .Ltl4_go
	s_mov_b32 s99, 0
	v_mov_b32_e32 v0, 0x4a00
.Ltl4_spin:
	global_load_dword v1, v0, s[94:95] sc1
	s_waitcnt vmcnt(0)
	v_readfirstlane_b32 s3, v1
	s_cmp_ge_u32 s3, 44
	s_cbranch_scc1 .Ltl4_rdy
	s_sleep 8
	s_add_u32 s99, s99, 1
	s_cmp_lt_u32 s99, 0x800
	s_cbranch_scc1 .Ltl4_spin
.Ltl4_rdy:
	s_sub_u32 s3, s2, 172
	s_mul_i32 s4, s3, 205
	s_lshr_b32 s4, s4, 11
	s_mul_i32 s5, s4, 10
	s_sub_u32 s92, s3, s5
	s_lshr_b32 s5, s4, 2
	s_add_u32 s47, s5, 64
	s_and_b32 s72, s4, 3
	s_min_u32 s5, s92, 2
	s_lshl_b32 s3, s92, 1
	s_add_u32 s3, s3, s5
	s_lshl_b32 s6, s3, 8
	s_mov_b32 s7, 0
	s_cmp_lt_u32 s92, 2
	s_cselect_b32 s73, 6, 4

.LBB0_408:
	s_add_i32 s42, s74, 1
	s_mov_b64 s[4:5], -1
	s_and_b64 vcc, exec, s[30:31]
	s_cbranch_vccz .LBB0_419
	s_mul_i32 s4, s42, s28
	s_mul_hi_u32 s5, s42, s29
	s_add_i32 s5, s5, s4
	s_mul_i32 s4, s42, s29
	s_add_u32 s4, s4, s2
	s_addc_u32 s5, s5, s36
	v_cmp_gt_i64_e32 vcc, s[4:5], v[140:141]
	s_mov_b64 s[8:9], -1
	s_and_b64 vcc, exec, vcc
	s_cbranch_vccz .LBB0_412
	s_add_u32 s6, s4, 0xffffff00
	s_addc_u32 s7, s5, -1
	v_cmp_gt_u64_e32 vcc, s[6:7], v[142:143]
	s_mov_b64 s[8:9], 0
	s_and_b64 vcc, exec, vcc
	s_mov_b64 s[6:7], 0
	s_mov_b32 s43, s81
	s_mov_b32 s44, s80
	s_mov_b32 s96, s78
	s_mov_b32 s45, s75
	s_mov_b32 s46, s79
	s_branch .LBB0_412
	s_and_b32 s5, s4, 0xff
	s_mulk_i32 s5, 0x75
	s_lshr_b32 s5, s5, 8
	s_sub_i32 s6, s4, s5
	s_bfe_u32 s6, s6, 0x70001
	s_add_i32 s6, s6, s5
	s_bfe_u32 s7, s6, 0x50003
	s_mul_i32 s7, s7, 11
	s_sub_i32 s7, s4, s7
	s_and_b32 s5, s6, 0xff
	s_and_b32 s46, s7, 0xff
	s_bfe_u32 s6, s6, 0x30005
	s_or_b32 s43, s6, 64
	s_bfe_u32 s44, s5, 0x20003
	s_lshl_b32 s96, s46, 8
	s_mov_b32 s45, 4
	s_mov_b64 s[6:7], -1

.LBB0_501:
	v_lshl_add_u64 v[34:35], v[20:21], 0, v[48:49]
	v_add_co_u32_e64 v80, s[0:1], s3, v34
	v_lshl_add_u64 v[36:37], v[24:25], 0, v[48:49]
	s_nop 0
	v_addc_co_u32_e64 v81, s[0:1], 0, v35, s[0:1]
	v_add_co_u32_e64 v96, s[0:1], s6, v34
	v_add_u32_e32 v232, 0x4000, v50
	s_nop 0
	v_addc_co_u32_e64 v97, s[0:1], 0, v35, s[0:1]
	v_add_co_u32_e64 v112, s[0:1], s7, v34
	global_load_dwordx4 v[52:55], v[36:37], off
	global_load_dwordx4 v[56:59], v[36:37], off offset:1024
	global_load_dwordx4 v[60:63], v[36:37], off offset:2048
	global_load_dwordx4 v[64:67], v[36:37], off offset:3072
	v_addc_co_u32_e64 v113, s[0:1], 0, v35, s[0:1]
	v_add_co_u32_e64 v128, s[0:1], s8, v34
	v_add_co_u32_e32 v36, vcc, 0xe600000, v34
	s_nop 0
	v_addc_co_u32_e64 v129, s[0:1], 0, v35, s[0:1]
	v_add_co_u32_e64 v146, s[0:1], s9, v34
	v_ashrrev_i32_e32 v233, 31, v232
	s_nop 0
	v_addc_co_u32_e64 v147, s[0:1], 0, v35, s[0:1]
	v_add_co_u32_e64 v162, s[0:1], s10, v34
	v_addc_co_u32_e32 v37, vcc, 0, v35, vcc
	s_nop 0
	v_addc_co_u32_e64 v163, s[0:1], 0, v35, s[0:1]
	v_add_co_u32_e64 v180, s[0:1], s11, v34
	v_lshlrev_b64 v[250:251], 11, v[232:233]
	s_nop 0
	v_addc_co_u32_e64 v181, s[0:1], 0, v35, s[0:1]
	v_add_co_u32_e64 v196, s[0:1], s12, v34
	v_ashrrev_i32_e32 v51, 2, v50
	s_nop 0
	v_addc_co_u32_e64 v197, s[0:1], 0, v35, s[0:1]
	v_add_co_u32_e64 v212, s[0:1], s13, v34
	v_lshl_add_u64 v[38:39], v[22:23], 0, v[48:49]
	s_nop 0
	v_addc_co_u32_e64 v213, s[0:1], 0, v35, s[0:1]
	v_add_co_u32_e64 v228, s[0:1], s14, v34
	v_add_u32_e32 v51, 8, v51
	s_nop 0
	v_addc_co_u32_e64 v229, s[0:1], 0, v35, s[0:1]
	global_load_dwordx4 v[68:71], v[80:81], off
	global_load_dwordx4 v[72:75], v[80:81], off offset:1024
	global_load_dwordx4 v[76:79], v[80:81], off offset:2048
	s_nop 0
	global_load_dwordx4 v[80:83], v[80:81], off offset:3072
	s_nop 0
	global_load_dwordx4 v[84:87], v[96:97], off
	global_load_dwordx4 v[88:91], v[96:97], off offset:1024
	global_load_dwordx4 v[92:95], v[96:97], off offset:2048
	s_nop 0
	global_load_dwordx4 v[96:99], v[96:97], off offset:3072
	s_nop 0
	global_load_dwordx4 v[100:103], v[112:113], off
	global_load_dwordx4 v[104:107], v[112:113], off offset:1024
	global_load_dwordx4 v[108:111], v[112:113], off offset:2048
	s_nop 0
	global_load_dwordx4 v[112:115], v[112:113], off offset:3072
	s_nop 0
	global_load_dwordx4 v[116:119], v[128:129], off
	global_load_dwordx4 v[120:123], v[128:129], off offset:1024
	global_load_dwordx4 v[124:127], v[128:129], off offset:2048
	s_nop 0
	global_load_dwordx4 v[128:131], v[128:129], off offset:3072
	s_nop 0
	global_load_dwordx4 v[132:135], v[146:147], off
	global_load_dwordx4 v[136:139], v[146:147], off offset:1024
	global_load_dwordx4 v[140:143], v[146:147], off offset:2048
	s_nop 0
	global_load_dwordx4 v[146:149], v[146:147], off offset:3072
	s_nop 0
	global_load_dwordx4 v[150:153], v[162:163], off
	global_load_dwordx4 v[154:157], v[162:163], off offset:1024
	global_load_dwordx4 v[158:161], v[162:163], off offset:2048
	s_nop 0
	global_load_dwordx4 v[162:165], v[162:163], off offset:3072
	s_nop 0
	global_load_dwordx4 v[166:169], v[180:181], off
	global_load_dwordx4 v[170:173], v[180:181], off offset:1024
	global_load_dwordx4 v[176:179], v[180:181], off offset:2048
	s_nop 0
	global_load_dwordx4 v[180:183], v[180:181], off offset:3072
	s_nop 0
	global_load_dwordx4 v[184:187], v[196:197], off
	global_load_dwordx4 v[188:191], v[196:197], off offset:1024
	global_load_dwordx4 v[192:195], v[196:197], off offset:2048
	s_nop 0
	global_load_dwordx4 v[196:199], v[196:197], off offset:3072
	s_nop 0
	global_load_dwordx4 v[200:203], v[212:213], off
	global_load_dwordx4 v[204:207], v[212:213], off offset:1024
	global_load_dwordx4 v[208:211], v[212:213], off offset:2048
	s_nop 0
	global_load_dwordx4 v[212:215], v[212:213], off offset:3072
	s_nop 0
	s_nop 0
	s_nop 0
	global_load_dwordx4 v[232:235], v[36:37], off
	global_load_dwordx4 v[236:239], v[36:37], off offset:1024
	global_load_dwordx4 v[240:243], v[36:37], off offset:2048
	global_load_dwordx4 v[244:247], v[36:37], off offset:3072
	v_add_co_u32_e64 v248, s[0:1], s16, v38
	v_add_u32_e32 v50, s30, v50
	s_nop 0
	v_addc_co_u32_e64 v249, s[0:1], 0, v39, s[0:1]
	v_mad_i64_i32 v[34:35], s[0:1], v51, s15, v[26:27]
	v_lshl_add_u64 v[38:39], v[34:35], 0, s[50:51]
	v_lshl_add_u64 v[36:37], v[34:35], 0, s[52:53]
	v_lshl_add_u64 v[34:35], v[18:19], 0, v[250:251]
	v_lshl_add_u64 v[250:251], v[38:39], 0, v[16:17]
	v_lshl_add_u64 v[252:253], v[36:37], 0, v[16:17]
	v_lshl_add_u64 v[20:21], v[20:21], 0, s[48:49]
	v_lshl_add_u64 v[22:23], v[22:23], 0, s[48:49]
	v_lshl_add_u64 v[24:25], v[24:25], 0, s[48:49]
	s_waitcnt vmcnt(0)
	v_pk_add_f32 v[54:55], v[54:55], v[234:235]
	v_pk_add_f32 v[52:53], v[52:53], v[232:233]
	v_pk_add_f32 v[58:59], v[58:59], v[238:239]
	v_pk_add_f32 v[56:57], v[56:57], v[236:237]
	v_pk_add_f32 v[62:63], v[62:63], v[242:243]
	v_pk_add_f32 v[60:61], v[60:61], v[240:241]
	v_pk_add_f32 v[66:67], v[66:67], v[246:247]
	v_pk_add_f32 v[64:65], v[64:65], v[244:245]
	v_pk_add_f32 v[54:55], v[54:55], v[70:71]
	v_pk_add_f32 v[52:53], v[52:53], v[68:69]
	v_pk_add_f32 v[58:59], v[58:59], v[74:75]
	v_pk_add_f32 v[56:57], v[56:57], v[72:73]
	v_pk_add_f32 v[62:63], v[62:63], v[78:79]
	v_pk_add_f32 v[60:61], v[60:61], v[76:77]
	v_pk_add_f32 v[66:67], v[66:67], v[82:83]
	v_pk_add_f32 v[64:65], v[64:65], v[80:81]
	v_pk_add_f32 v[54:55], v[54:55], v[86:87]
	v_pk_add_f32 v[52:53], v[52:53], v[84:85]
	v_pk_add_f32 v[58:59], v[58:59], v[90:91]
	v_pk_add_f32 v[56:57], v[56:57], v[88:89]
	v_pk_add_f32 v[62:63], v[62:63], v[94:95]
	v_pk_add_f32 v[60:61], v[60:61], v[92:93]
	v_pk_add_f32 v[66:67], v[66:67], v[98:99]
	v_pk_add_f32 v[64:65], v[64:65], v[96:97]
	v_pk_add_f32 v[54:55], v[54:55], v[102:103]
	v_pk_add_f32 v[52:53], v[52:53], v[100:101]
	v_pk_add_f32 v[58:59], v[58:59], v[106:107]
	v_pk_add_f32 v[56:57], v[56:57], v[104:105]
	v_pk_add_f32 v[62:63], v[62:63], v[110:111]
	v_pk_add_f32 v[60:61], v[60:61], v[108:109]
	v_pk_add_f32 v[66:67], v[66:67], v[114:115]
	v_pk_add_f32 v[64:65], v[64:65], v[112:113]
	v_pk_add_f32 v[54:55], v[54:55], v[118:119]
	v_pk_add_f32 v[52:53], v[52:53], v[116:117]
	v_pk_add_f32 v[58:59], v[58:59], v[122:123]
	v_pk_add_f32 v[56:57], v[56:57], v[120:121]
	v_pk_add_f32 v[62:63], v[62:63], v[126:127]
	v_pk_add_f32 v[60:61], v[60:61], v[124:125]
	v_pk_add_f32 v[66:67], v[66:67], v[130:131]
	v_pk_add_f32 v[64:65], v[64:65], v[128:129]
	v_pk_add_f32 v[54:55], v[54:55], v[134:135]
	v_pk_add_f32 v[52:53], v[52:53], v[132:133]
	v_pk_add_f32 v[58:59], v[58:59], v[138:139]
	v_pk_add_f32 v[56:57], v[56:57], v[136:137]
	v_pk_add_f32 v[62:63], v[62:63], v[142:143]
	v_pk_add_f32 v[60:61], v[60:61], v[140:141]
	v_pk_add_f32 v[66:67], v[66:67], v[148:149]
	v_pk_add_f32 v[64:65], v[64:65], v[146:147]
	v_pk_add_f32 v[54:55], v[54:55], v[152:153]
	v_pk_add_f32 v[52:53], v[52:53], v[150:151]
	v_pk_add_f32 v[58:59], v[58:59], v[156:157]
	v_pk_add_f32 v[56:57], v[56:57], v[154:155]
	v_pk_add_f32 v[62:63], v[62:63], v[160:161]
	v_pk_add_f32 v[60:61], v[60:61], v[158:159]
	v_pk_add_f32 v[66:67], v[66:67], v[164:165]
	v_pk_add_f32 v[64:65], v[64:65], v[162:163]
	v_pk_add_f32 v[54:55], v[54:55], v[168:169]
	v_pk_add_f32 v[52:53], v[52:53], v[166:167]
	v_pk_add_f32 v[58:59], v[58:59], v[172:173]
	v_pk_add_f32 v[56:57], v[56:57], v[170:171]
	v_pk_add_f32 v[62:63], v[62:63], v[178:179]
	v_pk_add_f32 v[60:61], v[60:61], v[176:177]
	v_pk_add_f32 v[66:67], v[66:67], v[182:183]
	v_pk_add_f32 v[64:65], v[64:65], v[180:181]
	v_pk_add_f32 v[54:55], v[54:55], v[186:187]
	v_pk_add_f32 v[52:53], v[52:53], v[184:185]
	v_pk_add_f32 v[58:59], v[58:59], v[190:191]
	v_pk_add_f32 v[56:57], v[56:57], v[188:189]
	v_pk_add_f32 v[62:63], v[62:63], v[194:195]
	v_pk_add_f32 v[60:61], v[60:61], v[192:193]
	v_pk_add_f32 v[66:67], v[66:67], v[198:199]
	v_pk_add_f32 v[64:65], v[64:65], v[196:197]
	v_pk_add_f32 v[54:55], v[54:55], v[202:203]
	v_pk_add_f32 v[52:53], v[52:53], v[200:201]
	v_pk_add_f32 v[58:59], v[58:59], v[206:207]
	v_pk_add_f32 v[56:57], v[56:57], v[204:205]
	v_pk_add_f32 v[62:63], v[62:63], v[210:211]
	v_pk_add_f32 v[60:61], v[60:61], v[208:209]
	v_pk_add_f32 v[66:67], v[66:67], v[214:215]
	v_pk_add_f32 v[64:65], v[64:65], v[212:213]
	global_store_dwordx4 v[248:249], v[52:55], off
	global_store_dwordx4 v[248:249], v[56:59], off offset:1024
	global_store_dwordx4 v[248:249], v[60:63], off offset:2048
	global_store_dwordx4 v[248:249], v[64:67], off offset:3072
	v_pk_mul_f32 v[68:69], v[54:55], v[54:55]
	v_pk_mul_f32 v[76:77], v[52:53], v[52:53]
	v_pk_mul_f32 v[70:71], v[58:59], v[58:59]
	v_pk_mul_f32 v[78:79], v[56:57], v[56:57]
	v_mul_f32_e32 v72, v61, v61
	v_mul_f32_e32 v74, v63, v63
	v_pk_mov_b32 v[80:81], v[76:77], v[68:69] op_sel:[1,0]
	v_mov_b32_e32 v77, v69
	v_pk_mov_b32 v[82:83], v[78:79], v[70:71] op_sel:[1,0]
	v_mov_b32_e32 v79, v71
	v_pk_fma_f32 v[84:85], v[60:61], v[60:61], v[72:73] op_sel_hi:[1,1,0]
	v_pk_fma_f32 v[86:87], v[62:63], v[62:63], v[74:75] op_sel_hi:[1,1,0]
	global_load_dwordx4 v[68:71], v[250:251], off
	global_load_dwordx4 v[72:75], v[252:253], off
	v_pk_add_f32 v[76:77], v[80:81], v[76:77]
	v_pk_add_f32 v[78:79], v[82:83], v[78:79]
	v_mul_f32_e32 v51, v64, v64
	v_mul_f32_e32 v88, v65, v65
	v_mul_f32_e32 v89, v66, v66
	v_mul_f32_e32 v90, v67, v67
	v_pk_add_f32 v[76:77], v[76:77], v[76:77] op_sel:[0,1] op_sel_hi:[1,0]
	v_pk_add_f32 v[78:79], v[78:79], v[78:79] op_sel:[0,1] op_sel_hi:[1,0]
	v_mov_b32_e32 v85, v89
	v_mov_b32_e32 v87, v90
	v_mov_b32_e32 v77, v51
	v_mov_b32_e32 v79, v88
	v_pk_add_f32 v[80:81], v[84:85], v[86:87]
	v_pk_add_f32 v[76:77], v[76:77], v[78:79]
	v_lshl_add_u64 v[232:233], v[38:39], 0, v[28:29]
	v_pk_add_f32 v[76:77], v[76:77], v[80:81]
	v_lshl_add_u64 v[234:235], v[36:37], 0, v[28:29]
	v_add_f32_e32 v51, v76, v77
	ds_bpermute_b32 v76, v40, v51
	s_waitcnt lgkmcnt(0)
	v_add_f32_e32 v51, v51, v76
	ds_bpermute_b32 v76, v41, v51
	s_waitcnt lgkmcnt(0)
	v_add_f32_e32 v51, v51, v76
	ds_bpermute_b32 v76, v42, v51
	s_waitcnt lgkmcnt(0)
	v_add_f32_e32 v51, v51, v76
	ds_bpermute_b32 v76, v43, v51
	s_waitcnt lgkmcnt(0)
	v_add_f32_e32 v51, v51, v76
	ds_bpermute_b32 v76, v44, v51
	s_waitcnt lgkmcnt(0)
	v_add_f32_e32 v51, v51, v76
	ds_bpermute_b32 v76, v45, v51
	s_waitcnt lgkmcnt(0)
	v_add_f32_e32 v51, v51, v76
	v_fmamk_f32 v51, v51, 0x3a800000, v46
	v_mul_f32_e32 v76, 0x4f800000, v51
	v_cmp_gt_f32_e32 vcc, s13, v51
	s_waitcnt vmcnt(1)
	v_pk_add_f32 v[68:69], v[68:69], 1.0 op_sel_hi:[1,0]
	v_cndmask_b32_e32 v51, v51, v76, vcc
	v_sqrt_f32_e32 v76, v51
	v_pk_add_f32 v[70:71], v[70:71], 1.0 op_sel_hi:[1,0]
	v_add_u32_e32 v77, -1, v76
	v_add_u32_e32 v78, 1, v76
	v_fma_f32 v79, -v77, v76, v51
	v_fma_f32 v80, -v78, v76, v51
	v_cmp_ge_f32_e64 s[0:1], 0, v79
	s_nop 1
	v_cndmask_b32_e64 v76, v76, v77, s[0:1]
	v_cmp_lt_f32_e64 s[0:1], 0, v80
	s_nop 1
	v_cndmask_b32_e64 v76, v76, v78, s[0:1]
	v_mul_f32_e32 v77, 0x37800000, v76
	v_cndmask_b32_e32 v76, v76, v77, vcc
	v_cmp_class_f32_e32 vcc, v51, v47
	s_nop 1
	v_cndmask_b32_e32 v51, v76, v51, vcc
	v_div_scale_f32 v76, s[0:1], v51, v51, 1.0
	v_rcp_f32_e32 v78, v76
	v_div_scale_f32 v77, vcc, 1.0, v51, 1.0
	v_fma_f32 v79, -v76, v78, 1.0
	v_fmac_f32_e32 v78, v79, v78
	v_mul_f32_e32 v79, v77, v78
	v_fma_f32 v80, -v76, v79, v77
	v_fmac_f32_e32 v79, v80, v78
	v_fma_f32 v76, -v76, v79, v77
	v_div_fmas_f32 v76, v76, v78, v79
	v_div_fixup_f32 v76, v76, v51, 1.0
	v_pk_mul_f32 v[52:53], v[52:53], v[76:77] op_sel_hi:[1,0]
	v_pk_mul_f32 v[54:55], v[54:55], v[76:77] op_sel_hi:[1,0]
	v_pk_mul_f32 v[52:53], v[0:1], v[52:53]
	v_pk_mul_f32 v[54:55], v[2:3], v[54:55]
	s_waitcnt vmcnt(0)
	v_pk_fma_f32 v[52:53], v[68:69], v[52:53], v[72:73]
	v_pk_fma_f32 v[54:55], v[70:71], v[54:55], v[74:75]
	v_cvt_pk_bf16_f32 v52, v52, v53
	v_pk_mul_f32 v[56:57], v[56:57], v[76:77] op_sel_hi:[1,0]
	v_cvt_pk_bf16_f32 v53, v54, v55
	global_store_dwordx2 v[34:35], v[52:53], off
	global_load_dwordx4 v[52:55], v[232:233], off
	s_nop 0
	global_load_dwordx4 v[68:71], v[234:235], off
	v_pk_mul_f32 v[58:59], v[58:59], v[76:77] op_sel_hi:[1,0]
	v_pk_mul_f32 v[56:57], v[4:5], v[56:57]
	v_pk_mul_f32 v[58:59], v[6:7], v[58:59]
	v_lshl_add_u64 v[72:73], v[38:39], 0, v[30:31]
	v_lshl_add_u64 v[74:75], v[36:37], 0, v[30:31]
	v_pk_mul_f32 v[60:61], v[60:61], v[76:77] op_sel_hi:[1,0]
	v_lshl_add_u64 v[38:39], v[38:39], 0, v[32:33]
	v_pk_mul_f32 v[60:61], v[8:9], v[60:61]
	v_cmp_lt_i32_e32 vcc, s17, v50
	s_or_b64 s[38:39], vcc, s[38:39]
	s_waitcnt vmcnt(1)
	v_pk_add_f32 v[52:53], v[52:53], 1.0 op_sel_hi:[1,0]
	v_pk_add_f32 v[54:55], v[54:55], 1.0 op_sel_hi:[1,0]
	s_waitcnt vmcnt(0)
	v_pk_fma_f32 v[52:53], v[52:53], v[56:57], v[68:69]
	v_pk_fma_f32 v[54:55], v[54:55], v[58:59], v[70:71]
	v_cvt_pk_bf16_f32 v52, v52, v53
	v_lshl_add_u64 v[68:69], v[36:37], 0, v[32:33]
	v_cvt_pk_bf16_f32 v53, v54, v55
	global_store_dwordx2 v[34:35], v[52:53], off offset:512
	global_load_dwordx4 v[52:55], v[72:73], off
	s_nop 0
	global_load_dwordx4 v[56:59], v[74:75], off
	v_pk_mul_f32 v[36:37], v[62:63], v[76:77] op_sel_hi:[1,0]
	s_waitcnt vmcnt(1)
	v_pk_add_f32 v[52:53], v[52:53], 1.0 op_sel_hi:[1,0]
	v_pk_mul_f32 v[36:37], v[10:11], v[36:37]
	v_pk_add_f32 v[54:55], v[54:55], 1.0 op_sel_hi:[1,0]
	s_waitcnt vmcnt(0)
	v_pk_fma_f32 v[52:53], v[60:61], v[52:53], v[56:57]
	v_pk_fma_f32 v[36:37], v[36:37], v[54:55], v[58:59]
	v_cvt_pk_bf16_f32 v52, v52, v53
	v_pk_mul_f32 v[58:59], v[64:65], v[76:77] op_sel_hi:[1,0]
	v_cvt_pk_bf16_f32 v53, v36, v37
	global_store_dwordx2 v[34:35], v[52:53], off offset:1024
	global_load_dwordx4 v[36:39], v[38:39], off
	s_nop 0
	global_load_dwordx4 v[52:55], v[68:69], off
	v_pk_mul_f32 v[56:57], v[66:67], v[76:77] op_sel_hi:[1,0]
	v_pk_mul_f32 v[58:59], v[12:13], v[58:59]
	v_pk_mul_f32 v[56:57], v[14:15], v[56:57]
	s_waitcnt vmcnt(1)
	v_pk_add_f32 v[36:37], v[36:37], 1.0 op_sel_hi:[1,0]
	v_pk_add_f32 v[38:39], v[38:39], 1.0 op_sel_hi:[1,0]
	s_waitcnt vmcnt(0)
	v_pk_fma_f32 v[36:37], v[58:59], v[36:37], v[52:53]
	v_pk_fma_f32 v[38:39], v[56:57], v[38:39], v[54:55]
	v_cvt_pk_bf16_f32 v36, v36, v37
	s_nop 0
	v_cvt_pk_bf16_f32 v37, v38, v39
	global_store_dwordx2 v[34:35], v[36:37], off offset:1536
	s_andn2_b64 exec, exec, s[38:39]
	s_cbranch_execnz .LBB0_501

.LBB0_715:
	s_cmp_gt_i32 s34, 48
	s_cselect_b32 s0, 24, 0
	s_cmp_lt_i32 s2, s0
	s_cbranch_scc1 .LBB0_782
	s_sub_i32 s1, s34, s0
	s_abs_i32 s3, s1
	s_waitcnt vmcnt(0)
	v_cvt_f32_u32_e32 v0, s3
	s_sub_i32 s5, 0, s3
	s_sub_i32 s4, s2, s0
	s_ashr_i32 s0, s1, 31
	v_rcp_iflag_f32_e32 v0, v0
	s_nop 0
	v_mul_f32_e32 v0, 0x4f7ffffe, v0
	v_cvt_u32_f32_e32 v0, v0
	s_nop 0
	v_readfirstlane_b32 s6, v0
	s_mul_i32 s5, s5, s6
	s_mul_hi_u32 s5, s6, s5
	s_add_i32 s6, s6, s5
	s_lshr_b32 s5, s6, 22
	s_mul_i32 s6, s5, s3
	s_sub_i32 s6, 0x400, s6
	s_add_i32 s7, s5, 1
	s_sub_i32 s8, s6, s3
	s_cmp_ge_u32 s6, s3
	s_cselect_b32 s5, s7, s5
	s_cselect_b32 s6, s8, s6
	s_add_i32 s7, s5, 1
	s_cmp_ge_u32 s6, s3
	s_cselect_b32 s3, s7, s5
	s_xor_b32 s3, s3, s0
	s_sub_i32 s5, s3, s0
	s_mul_i32 s0, s5, s1
	s_sub_i32 s6, 0x400, s0
	s_cmp_lt_i32 s4, s6
	s_mul_i32 s3, s5, s4
	s_cselect_b64 s[0:1], -1, 0
	s_min_i32 s4, s4, s6
	s_add_i32 s3, s4, s3
	s_cmp_lg_u64 s[0:1], 0
	s_addc_u32 s10, s3, s5
	s_add_i32 s1, s3, 1
	s_add_i32 s4, s10, 1
	s_ashr_i32 s0, s1, 1
	s_ashr_i32 s11, s4, 1
	s_cmp_ge_i32 s0, s11
	s_cbranch_scc1 .LBB0_726
	v_readfirstlane_b32 s4, v175
	s_lshr_b32 s8, s4, 6
	s_ashr_i32 s4, s1, 7
	s_ashr_i32 s5, s4, 31
	s_lshl_b32 s6, s0, 17
	s_lshl_b64 s[4:5], s[4:5], 21
	s_and_b32 s6, s6, 0x1e0000
	s_lshl_b32 s1, s0, 16
	s_or_b32 s4, s4, s6
	s_add_u32 s6, s36, s4
	s_addc_u32 s7, s37, s5
	s_lshl_b32 s12, s0, 4
	s_lshl_b32 s9, s0, 3
	s_and_b32 s12, s12, 0x300
	s_add_u32 s6, s6, s12
	s_addc_u32 s7, s7, 0
	s_add_u32 s4, s38, s4
	v_lshlrev_b32_e32 v0, 7, v175
	s_addc_u32 s5, s39, s5
	v_and_b32_e32 v36, 0x1fe00, v0
	v_lshlrev_b32_e32 v2, 5, v175
	s_add_u32 s4, s4, s12
	v_mov_b32_e32 v33, 0
	v_lshlrev_b32_e32 v32, 1, v36
	v_and_b32_e32 v42, 0x60, v2
	s_addc_u32 s5, s5, 0
	v_lshl_add_u64 v[0:1], s[6:7], 0, v[32:33]
	v_lshlrev_b32_e32 v34, 1, v42
	v_mov_b32_e32 v35, v33
	v_lshl_add_u64 v[16:17], s[4:5], 0, v[32:33]
	v_lshl_add_u64 v[12:13], v[0:1], 0, v[34:35]
	v_lshl_add_u64 v[28:29], v[16:17], 0, v[34:35]
	global_load_dwordx4 v[0:3], v[12:13], off offset:48
	global_load_dwordx4 v[4:7], v[12:13], off offset:32
	global_load_dwordx4 v[8:11], v[12:13], off offset:16
	s_nop 0
	global_load_dwordx4 v[12:15], v[12:13], off
	s_nop 0
	global_load_dwordx4 v[16:19], v[28:29], off offset:48
	global_load_dwordx4 v[20:23], v[28:29], off offset:32
	global_load_dwordx4 v[24:27], v[28:29], off offset:16
	s_nop 0
	global_load_dwordx4 v[28:31], v[28:29], off
	v_and_b32_e32 v32, 15, v175
	v_lshrrev_b32_e32 v35, 2, v175
	v_add_u32_e32 v37, 0, v34
	v_lshl_add_u32 v34, v32, 1, 0
	v_sub_u32_e32 v38, 0x7f, v35
	s_movk_i32 s4, 0x108
	v_mul_u32_u24_e32 v43, 0x108, v35
	v_and_b32_e32 v35, 12, v35
	v_lshlrev_b32_e32 v32, 7, v32
	s_add_i32 s13, s1, 0x10000
	s_ashr_i32 s1, s0, 31
	v_mad_u32_u24 v39, v35, s4, v34
	s_lshl_b64 s[4:5], s[0:1], 16
	v_lshl_or_b32 v40, s8, 11, v32
	v_cvt_f32_i32_e32 v38, v38
	v_lshl_add_u32 v44, s8, 5, v34
	v_mul_u32_u24_e32 v45, 0x108, v35
	v_and_or_b32 v34, v175, 48, s4
	v_mov_b32_e32 v35, s5
	v_ashrrev_i32_e32 v41, 31, v40
	v_lshl_add_u64 v[34:35], v[40:41], 2, v[34:35]
	v_lshl_add_u64 v[34:35], s[94:95], 0, v[34:35]
	s_mov_b64 s[4:5], 0x100100
	s_add_i32 s12, s9, 8
	v_lshl_add_u64 v[34:35], v[34:35], 0, s[4:5]
	v_add_u32_e32 v40, v37, v43
	v_lshlrev_b32_e32 v32, 1, v36
	v_lshlrev_b32_e32 v36, 1, v42
	v_add_u32_e32 v41, v44, v45
	s_mov_b32 s1, 0x5040100
	s_mov_b64 s[4:5], 0x10000
	v_mov_b32_e32 v42, 0xbbb906ce
	v_mov_b32_e32 v43, 0xbc3963dd
	s_branch .LBB0_719
.Lp_tramp:
	s_branch .Lp_reentry
.LBB0_718:
	s_waitcnt lgkmcnt(0)
	s_barrier
	ds_read_u16 v37, v39 offset:38640
	ds_read_u16 v48, v41
	ds_read_u16 v52, v41 offset:264
	ds_read_u16 v49, v41 offset:528
	ds_read_u16 v53, v41 offset:792
	ds_read_u16 v50, v41 offset:4224
	ds_read_u16 v54, v41 offset:4488
	ds_read_u16 v51, v41 offset:4752
	ds_read_u16 v55, v41 offset:5016
	ds_read_u16 v44, v39 offset:38544
	ds_read_u16 v56, v39 offset:38576
	ds_read_u16 v57, v39 offset:38608
	ds_read_u16 v64, v39 offset:38672
	ds_read_u16 v68, v39 offset:38704
	ds_read_u16 v72, v39 offset:38736
	ds_read_u16 v76, v39 offset:38768
	ds_read_u16 v45, v39 offset:38808
	ds_read_u16 v58, v39 offset:38840
	ds_read_u16 v59, v39 offset:38872
	ds_read_u16 v60, v39 offset:38904
	ds_read_u16 v65, v39 offset:38936
	ds_read_u16 v69, v39 offset:38968
	ds_read_u16 v73, v39 offset:39000
	ds_read_u16 v77, v39 offset:39032
	s_waitcnt lgkmcnt(7)
	v_perm_b32 v47, v45, v44, s1
	ds_read_u16 v44, v39 offset:38016
	ds_read_u16 v61, v39 offset:38048
	ds_read_u16 v62, v39 offset:38080
	ds_read_u16 v66, v39 offset:38112
	ds_read_u16 v70, v39 offset:38144
	ds_read_u16 v74, v39 offset:38176
	ds_read_u16 v78, v39 offset:38208
	ds_read_u16 v80, v39 offset:38240
	ds_read_u16 v45, v39 offset:38280
	ds_read_u16 v63, v39 offset:38312
	ds_read_u16 v67, v39 offset:38344
	ds_read_u16 v71, v39 offset:38376
	ds_read_u16 v75, v39 offset:38408
	ds_read_u16 v79, v39 offset:38440
	ds_read_u16 v81, v39 offset:38472
	ds_read_u16 v82, v39 offset:38504
	s_waitcnt lgkmcnt(7)
	v_perm_b32 v46, v45, v44, s1
	ds_read_u16 v44, v39 offset:34320
	ds_read_u16 v83, v39 offset:34352
	ds_read_u16 v84, v39 offset:34384
	ds_read_u16 v85, v39 offset:34416
	ds_read_u16 v86, v39 offset:34448
	ds_read_u16 v87, v39 offset:34480
	ds_read_u16 v88, v39 offset:34512
	ds_read_u16 v89, v39 offset:34544
	ds_read_u16 v45, v39 offset:34584
	ds_read_u16 v90, v39 offset:34616
	ds_read_u16 v91, v39 offset:34648
	ds_read_u16 v92, v39 offset:34680
	ds_read_u16 v93, v39 offset:34712
	ds_read_u16 v94, v39 offset:34744
	ds_read_u16 v95, v39 offset:34776
	ds_read_u16 v96, v39 offset:34808
	s_waitcnt lgkmcnt(7)
	v_perm_b32 v45, v45, v44, s1
	ds_read_u16 v44, v39 offset:33792
	ds_read_u16 v97, v39 offset:33824
	ds_read_u16 v98, v39 offset:33856
	ds_read_u16 v99, v39 offset:33888
	ds_read_u16 v100, v39 offset:33920
	ds_read_u16 v101, v39 offset:33952
	ds_read_u16 v102, v39 offset:33984
	ds_read_u16 v103, v39 offset:34016
	ds_read_u16 v104, v39 offset:34056
	ds_read_u16 v105, v39 offset:34088
	ds_read_u16 v106, v39 offset:34120
	ds_read_u16 v107, v39 offset:34152
	ds_read_u16 v108, v39 offset:34184
	ds_read_u16 v109, v39 offset:34216
	ds_read_u16 v110, v39 offset:34248
	ds_read_u16 v111, v39 offset:34280
	s_waitcnt lgkmcnt(7)
	v_perm_b32 v44, v104, v44, s1
	v_perm_b32 v51, v55, v51, s1
	v_perm_b32 v50, v54, v50, s1
	v_perm_b32 v49, v53, v49, s1
	v_perm_b32 v48, v52, v48, s1
	v_perm_b32 v55, v58, v56, s1
	v_perm_b32 v54, v63, v61, s1
	v_perm_b32 v53, v90, v83, s1
	s_waitcnt lgkmcnt(6)
	v_perm_b32 v52, v105, v97, s1
	v_perm_b32 v59, v59, v57, s1
	v_perm_b32 v58, v67, v62, s1
	v_perm_b32 v57, v91, v84, s1
	s_waitcnt lgkmcnt(5)
	v_perm_b32 v56, v106, v98, s1
	v_perm_b32 v63, v60, v37, s1
	v_perm_b32 v62, v71, v66, s1
	v_perm_b32 v61, v92, v85, s1
	s_waitcnt lgkmcnt(4)
	v_perm_b32 v60, v107, v99, s1
	v_perm_b32 v67, v65, v64, s1
	v_perm_b32 v66, v75, v70, s1
	v_perm_b32 v65, v93, v86, s1
	s_waitcnt lgkmcnt(3)
	v_perm_b32 v64, v108, v100, s1
	v_perm_b32 v71, v69, v68, s1
	v_perm_b32 v70, v79, v74, s1
	v_perm_b32 v69, v94, v87, s1
	s_waitcnt lgkmcnt(2)
	v_perm_b32 v68, v109, v101, s1
	v_perm_b32 v75, v73, v72, s1
	v_perm_b32 v74, v81, v78, s1
	v_perm_b32 v73, v95, v88, s1
	s_waitcnt lgkmcnt(1)
	v_perm_b32 v72, v110, v102, s1
	v_perm_b32 v79, v77, v76, s1
	v_perm_b32 v78, v82, v80, s1
	v_perm_b32 v77, v96, v89, s1
	s_waitcnt lgkmcnt(0)
	v_perm_b32 v76, v111, v103, s1
	v_mfma_f32_16x16x32_bf16 v[44:47], v[44:47], v[48:51], 0
	s_add_i32 s12, s12, 8
	s_add_i32 s13, s13, 0x10000
	s_andn2_b64 vcc, exec, s[8:9]
	v_mfma_f32_16x16x32_bf16 v[52:55], v[52:55], v[48:51], 0
	v_mfma_f32_16x16x32_bf16 v[56:59], v[56:59], v[48:51], 0
	v_mfma_f32_16x16x32_bf16 v[60:63], v[60:63], v[48:51], 0
	v_mfma_f32_16x16x32_bf16 v[64:67], v[64:67], v[48:51], 0
	v_mfma_f32_16x16x32_bf16 v[68:71], v[68:71], v[48:51], 0
	v_mfma_f32_16x16x32_bf16 v[72:75], v[72:75], v[48:51], 0
	v_mfma_f32_16x16x32_bf16 v[48:51], v[76:79], v[48:51], 0
	ds_read_u16 v37, v41 offset:8448
	ds_read_u16 v80, v41 offset:8712
	ds_read_u16 v81, v41 offset:8976
	ds_read_u16 v84, v41 offset:9240
	ds_read_u16 v82, v41 offset:12672
	ds_read_u16 v85, v41 offset:12936
	ds_read_u16 v83, v41 offset:13200
	ds_read_u16 v86, v41 offset:13464
	ds_read_u16 v76, v39 offset:46992
	ds_read_u16 v87, v39 offset:47024
	ds_read_u16 v88, v39 offset:47056
	ds_read_u16 v89, v39 offset:47088
	ds_read_u16 v90, v39 offset:47120
	ds_read_u16 v91, v39 offset:47152
	ds_read_u16 v92, v39 offset:47184
	ds_read_u16 v93, v39 offset:47216
	ds_read_u16 v77, v39 offset:47256
	ds_read_u16 v94, v39 offset:47288
	ds_read_u16 v95, v39 offset:47320
	ds_read_u16 v96, v39 offset:47352
	ds_read_u16 v97, v39 offset:47384
	ds_read_u16 v98, v39 offset:47416
	ds_read_u16 v99, v39 offset:47448
	ds_read_u16 v100, v39 offset:47480
	s_waitcnt lgkmcnt(7)
	v_perm_b32 v79, v77, v76, s1
	ds_read_u16 v76, v39 offset:46464
	ds_read_u16 v101, v39 offset:46496
	ds_read_u16 v102, v39 offset:46528
	ds_read_u16 v103, v39 offset:46560
	ds_read_u16 v104, v39 offset:46592
	ds_read_u16 v105, v39 offset:46624
	ds_read_u16 v106, v39 offset:46656
	ds_read_u16 v107, v39 offset:46688
	ds_read_u16 v77, v39 offset:46728
	ds_read_u16 v108, v39 offset:46760
	ds_read_u16 v109, v39 offset:46792
	ds_read_u16 v110, v39 offset:46824
	ds_read_u16 v111, v39 offset:46856
	ds_read_u16 v112, v39 offset:46888
	ds_read_u16 v113, v39 offset:46920
	ds_read_u16 v114, v39 offset:46952
	s_waitcnt lgkmcnt(7)
	v_perm_b32 v78, v77, v76, s1
	ds_read_u16 v76, v39 offset:42768
	ds_read_u16 v115, v39 offset:42800
	ds_read_u16 v116, v39 offset:42832
	ds_read_u16 v117, v39 offset:42864
	ds_read_u16 v118, v39 offset:42896
	ds_read_u16 v119, v39 offset:42928
	ds_read_u16 v120, v39 offset:42960
	ds_read_u16 v121, v39 offset:42992
	ds_read_u16 v77, v39 offset:43032
	ds_read_u16 v122, v39 offset:43064
	ds_read_u16 v123, v39 offset:43096
	ds_read_u16 v124, v39 offset:43128
	ds_read_u16 v125, v39 offset:43160
	ds_read_u16 v126, v39 offset:43192
	ds_read_u16 v127, v39 offset:43224
	ds_read_u16 v128, v39 offset:43256
	s_waitcnt lgkmcnt(7)
	v_perm_b32 v77, v77, v76, s1
	ds_read_u16 v76, v39 offset:42240
	ds_read_u16 v129, v39 offset:42272
	ds_read_u16 v130, v39 offset:42304
	ds_read_u16 v131, v39 offset:42336
	ds_read_u16 v132, v39 offset:42368
	ds_read_u16 v133, v39 offset:42400
	ds_read_u16 v134, v39 offset:42432
	ds_read_u16 v135, v39 offset:42464
	ds_read_u16 v136, v39 offset:42504
	ds_read_u16 v137, v39 offset:42536
	ds_read_u16 v138, v39 offset:42568
	ds_read_u16 v139, v39 offset:42600
	ds_read_u16 v140, v39 offset:42632
	ds_read_u16 v141, v39 offset:42664
	ds_read_u16 v142, v39 offset:42696
	ds_read_u16 v143, v39 offset:42728
	s_waitcnt lgkmcnt(7)
	v_perm_b32 v76, v136, v76, s1
	v_perm_b32 v83, v86, v83, s1
	v_perm_b32 v82, v85, v82, s1
	v_perm_b32 v81, v84, v81, s1
	v_perm_b32 v80, v80, v37, s1
	s_nop 1
	v_mfma_f32_16x16x32_bf16 v[44:47], v[76:79], v[80:83], v[44:47]
	v_perm_b32 v79, v94, v87, s1
	v_perm_b32 v78, v108, v101, s1
	v_perm_b32 v77, v122, v115, s1
	s_waitcnt lgkmcnt(6)
	v_perm_b32 v76, v137, v129, s1
	s_nop 1
	v_mfma_f32_16x16x32_bf16 v[52:55], v[76:79], v[80:83], v[52:55]
	v_perm_b32 v79, v95, v88, s1
	v_perm_b32 v78, v109, v102, s1
	v_perm_b32 v77, v123, v116, s1
	s_waitcnt lgkmcnt(5)
	v_perm_b32 v76, v138, v130, s1
	s_nop 1
	v_mfma_f32_16x16x32_bf16 v[56:59], v[76:79], v[80:83], v[56:59]
	v_perm_b32 v79, v96, v89, s1
	v_perm_b32 v78, v110, v103, s1
	v_perm_b32 v77, v124, v117, s1
	s_waitcnt lgkmcnt(4)
	v_perm_b32 v76, v139, v131, s1
	s_nop 1
	v_mfma_f32_16x16x32_bf16 v[60:63], v[76:79], v[80:83], v[60:63]
	v_perm_b32 v79, v97, v90, s1
	v_perm_b32 v78, v111, v104, s1
	v_perm_b32 v77, v125, v118, s1
	s_waitcnt lgkmcnt(3)
	v_perm_b32 v76, v140, v132, s1
	s_nop 1
	v_mfma_f32_16x16x32_bf16 v[64:67], v[76:79], v[80:83], v[64:67]
	v_perm_b32 v79, v98, v91, s1
	v_perm_b32 v78, v112, v105, s1
	v_perm_b32 v77, v126, v119, s1
	s_waitcnt lgkmcnt(2)
	v_perm_b32 v76, v141, v133, s1
	s_nop 1
	v_mfma_f32_16x16x32_bf16 v[68:71], v[76:79], v[80:83], v[68:71]
	v_perm_b32 v79, v99, v92, s1
	v_perm_b32 v78, v113, v106, s1
	v_perm_b32 v77, v127, v120, s1
	s_waitcnt lgkmcnt(1)
	v_perm_b32 v76, v142, v134, s1
	s_nop 1
	v_mfma_f32_16x16x32_bf16 v[72:75], v[76:79], v[80:83], v[72:75]
	v_perm_b32 v79, v100, v93, s1
	v_perm_b32 v78, v114, v107, s1
	v_perm_b32 v77, v128, v121, s1
	s_waitcnt lgkmcnt(0)
	v_perm_b32 v76, v143, v135, s1
	s_nop 1
	v_mfma_f32_16x16x32_bf16 v[48:51], v[76:79], v[80:83], v[48:51]
	ds_read_u16 v37, v41 offset:16896
	ds_read_u16 v80, v41 offset:17160
	ds_read_u16 v81, v41 offset:17424
	ds_read_u16 v84, v41 offset:17688
	ds_read_u16 v82, v41 offset:21120
	ds_read_u16 v85, v41 offset:21384
	ds_read_u16 v83, v41 offset:21648
	ds_read_u16 v86, v41 offset:21912
	ds_read_u16 v76, v39 offset:55440
	ds_read_u16 v87, v39 offset:55472
	ds_read_u16 v88, v39 offset:55504
	ds_read_u16 v89, v39 offset:55536
	ds_read_u16 v90, v39 offset:55568
	ds_read_u16 v91, v39 offset:55600
	ds_read_u16 v92, v39 offset:55632
	ds_read_u16 v93, v39 offset:55664
	ds_read_u16 v77, v39 offset:55704
	ds_read_u16 v94, v39 offset:55736
	ds_read_u16 v95, v39 offset:55768
	ds_read_u16 v96, v39 offset:55800
	ds_read_u16 v97, v39 offset:55832
	ds_read_u16 v98, v39 offset:55864
	ds_read_u16 v99, v39 offset:55896
	ds_read_u16 v100, v39 offset:55928
	s_waitcnt lgkmcnt(7)
	v_perm_b32 v79, v77, v76, s1
	ds_read_u16 v76, v39 offset:54912
	ds_read_u16 v101, v39 offset:54944
	ds_read_u16 v102, v39 offset:54976
	ds_read_u16 v103, v39 offset:55008
	ds_read_u16 v104, v39 offset:55040
	ds_read_u16 v105, v39 offset:55072
	ds_read_u16 v106, v39 offset:55104
	ds_read_u16 v107, v39 offset:55136
	ds_read_u16 v77, v39 offset:55176
	ds_read_u16 v108, v39 offset:55208
	ds_read_u16 v109, v39 offset:55240
	ds_read_u16 v110, v39 offset:55272
	ds_read_u16 v111, v39 offset:55304
	ds_read_u16 v112, v39 offset:55336
	ds_read_u16 v113, v39 offset:55368
	ds_read_u16 v114, v39 offset:55400
	s_waitcnt lgkmcnt(7)
	v_perm_b32 v78, v77, v76, s1
	ds_read_u16 v76, v39 offset:51216
	ds_read_u16 v115, v39 offset:51248
	ds_read_u16 v116, v39 offset:51280
	ds_read_u16 v117, v39 offset:51312
	ds_read_u16 v118, v39 offset:51344
	ds_read_u16 v119, v39 offset:51376
	ds_read_u16 v120, v39 offset:51408
	ds_read_u16 v121, v39 offset:51440
	ds_read_u16 v77, v39 offset:51480
	ds_read_u16 v122, v39 offset:51512
	ds_read_u16 v123, v39 offset:51544
	ds_read_u16 v124, v39 offset:51576
	ds_read_u16 v125, v39 offset:51608
	ds_read_u16 v126, v39 offset:51640
	ds_read_u16 v127, v39 offset:51672
	ds_read_u16 v128, v39 offset:51704
	s_waitcnt lgkmcnt(7)
	v_perm_b32 v77, v77, v76, s1
	ds_read_u16 v76, v39 offset:50688
	ds_read_u16 v129, v39 offset:50720
	ds_read_u16 v130, v39 offset:50752
	ds_read_u16 v131, v39 offset:50784
	ds_read_u16 v132, v39 offset:50816
	ds_read_u16 v133, v39 offset:50848
	ds_read_u16 v134, v39 offset:50880
	ds_read_u16 v135, v39 offset:50912
	ds_read_u16 v136, v39 offset:50952
	ds_read_u16 v137, v39 offset:50984
	ds_read_u16 v138, v39 offset:51016
	ds_read_u16 v139, v39 offset:51048
	ds_read_u16 v140, v39 offset:51080
	ds_read_u16 v141, v39 offset:51112
	ds_read_u16 v142, v39 offset:51144
	ds_read_u16 v143, v39 offset:51176
	s_waitcnt lgkmcnt(7)
	v_perm_b32 v76, v136, v76, s1
	v_perm_b32 v83, v86, v83, s1
	v_perm_b32 v82, v85, v82, s1
	v_perm_b32 v81, v84, v81, s1
	v_perm_b32 v80, v80, v37, s1
	s_nop 1
	v_mfma_f32_16x16x32_bf16 v[44:47], v[76:79], v[80:83], v[44:47]
	v_perm_b32 v79, v94, v87, s1
	v_perm_b32 v78, v108, v101, s1
	v_perm_b32 v77, v122, v115, s1
	s_waitcnt lgkmcnt(6)
	v_perm_b32 v76, v137, v129, s1
	s_nop 1
	v_mfma_f32_16x16x32_bf16 v[52:55], v[76:79], v[80:83], v[52:55]
	v_perm_b32 v79, v95, v88, s1
	v_perm_b32 v78, v109, v102, s1
	v_perm_b32 v77, v123, v116, s1
	s_waitcnt lgkmcnt(5)
	v_perm_b32 v76, v138, v130, s1
	s_nop 1
	v_mfma_f32_16x16x32_bf16 v[56:59], v[76:79], v[80:83], v[56:59]
	v_perm_b32 v79, v96, v89, s1
	v_perm_b32 v78, v110, v103, s1
	v_perm_b32 v77, v124, v117, s1
	s_waitcnt lgkmcnt(4)
	v_perm_b32 v76, v139, v131, s1
	s_nop 1
	v_mfma_f32_16x16x32_bf16 v[60:63], v[76:79], v[80:83], v[60:63]
	v_perm_b32 v79, v97, v90, s1
	v_perm_b32 v78, v111, v104, s1
	v_perm_b32 v77, v125, v118, s1
	s_waitcnt lgkmcnt(3)
	v_perm_b32 v76, v140, v132, s1
	s_nop 1
	v_mfma_f32_16x16x32_bf16 v[64:67], v[76:79], v[80:83], v[64:67]
	v_perm_b32 v79, v98, v91, s1
	v_perm_b32 v78, v112, v105, s1
	v_perm_b32 v77, v126, v119, s1
	s_waitcnt lgkmcnt(2)
	v_perm_b32 v76, v141, v133, s1
	s_nop 1
	v_mfma_f32_16x16x32_bf16 v[68:71], v[76:79], v[80:83], v[68:71]
	v_perm_b32 v79, v99, v92, s1
	v_perm_b32 v78, v113, v106, s1
	v_perm_b32 v77, v127, v120, s1
	s_waitcnt lgkmcnt(1)
	v_perm_b32 v76, v142, v134, s1
	s_nop 1
	v_mfma_f32_16x16x32_bf16 v[72:75], v[76:79], v[80:83], v[72:75]
	v_perm_b32 v79, v100, v93, s1
	v_perm_b32 v78, v114, v107, s1
	v_perm_b32 v77, v128, v121, s1
	s_waitcnt lgkmcnt(0)
	v_perm_b32 v76, v143, v135, s1
	s_nop 1
	v_mfma_f32_16x16x32_bf16 v[48:51], v[76:79], v[80:83], v[48:51]
	ds_read_u16 v37, v41 offset:25344
	ds_read_u16 v80, v41 offset:25608
	ds_read_u16 v81, v41 offset:25872
	ds_read_u16 v84, v41 offset:26136
	ds_read_u16 v82, v41 offset:29568
	ds_read_u16 v85, v41 offset:29832
	ds_read_u16 v83, v41 offset:30096
	ds_read_u16 v86, v41 offset:30360
	ds_read_u16 v76, v39 offset:63888
	ds_read_u16 v87, v39 offset:63920
	ds_read_u16 v88, v39 offset:63952
	ds_read_u16 v89, v39 offset:63984
	ds_read_u16 v90, v39 offset:64016
	ds_read_u16 v91, v39 offset:64048
	ds_read_u16 v92, v39 offset:64080
	ds_read_u16 v93, v39 offset:64112
	ds_read_u16 v77, v39 offset:64152
	ds_read_u16 v94, v39 offset:64184
	ds_read_u16 v95, v39 offset:64216
	ds_read_u16 v96, v39 offset:64248
	ds_read_u16 v97, v39 offset:64280
	ds_read_u16 v98, v39 offset:64312
	ds_read_u16 v99, v39 offset:64344
	ds_read_u16 v100, v39 offset:64376
	s_waitcnt lgkmcnt(7)
	v_perm_b32 v79, v77, v76, s1
	ds_read_u16 v76, v39 offset:63360
	ds_read_u16 v101, v39 offset:63392
	ds_read_u16 v102, v39 offset:63424
	ds_read_u16 v103, v39 offset:63456
	ds_read_u16 v104, v39 offset:63488
	ds_read_u16 v105, v39 offset:63520
	ds_read_u16 v106, v39 offset:63552
	ds_read_u16 v107, v39 offset:63584
	ds_read_u16 v77, v39 offset:63624
	ds_read_u16 v108, v39 offset:63656
	ds_read_u16 v109, v39 offset:63688
	ds_read_u16 v110, v39 offset:63720
	ds_read_u16 v111, v39 offset:63752
	ds_read_u16 v112, v39 offset:63784
	ds_read_u16 v113, v39 offset:63816
	ds_read_u16 v114, v39 offset:63848
	s_waitcnt lgkmcnt(7)
	v_perm_b32 v78, v77, v76, s1
	ds_read_u16 v76, v39 offset:59664
	ds_read_u16 v115, v39 offset:59696
	ds_read_u16 v116, v39 offset:59728
	ds_read_u16 v117, v39 offset:59760
	ds_read_u16 v118, v39 offset:59792
	ds_read_u16 v119, v39 offset:59824
	ds_read_u16 v120, v39 offset:59856
	ds_read_u16 v121, v39 offset:59888
	ds_read_u16 v77, v39 offset:59928
	ds_read_u16 v122, v39 offset:59960
	ds_read_u16 v123, v39 offset:59992
	ds_read_u16 v124, v39 offset:60024
	ds_read_u16 v125, v39 offset:60056
	ds_read_u16 v126, v39 offset:60088
	ds_read_u16 v127, v39 offset:60120
	ds_read_u16 v128, v39 offset:60152
	s_waitcnt lgkmcnt(7)
	v_perm_b32 v77, v77, v76, s1
	ds_read_u16 v76, v39 offset:59136
	ds_read_u16 v129, v39 offset:59168
	ds_read_u16 v130, v39 offset:59200
	ds_read_u16 v131, v39 offset:59232
	ds_read_u16 v132, v39 offset:59264
	ds_read_u16 v133, v39 offset:59296
	ds_read_u16 v134, v39 offset:59328
	ds_read_u16 v135, v39 offset:59360
	ds_read_u16 v136, v39 offset:59400
	ds_read_u16 v137, v39 offset:59432
	ds_read_u16 v138, v39 offset:59464
	ds_read_u16 v139, v39 offset:59496
	ds_read_u16 v140, v39 offset:59528
	ds_read_u16 v141, v39 offset:59560
	ds_read_u16 v142, v39 offset:59592
	ds_read_u16 v143, v39 offset:59624
	s_waitcnt lgkmcnt(7)
	v_perm_b32 v76, v136, v76, s1
	v_perm_b32 v83, v86, v83, s1
	v_perm_b32 v82, v85, v82, s1
	v_perm_b32 v81, v84, v81, s1
	v_perm_b32 v80, v80, v37, s1
	s_nop 1
	v_mfma_f32_16x16x32_bf16 v[44:47], v[76:79], v[80:83], v[44:47]
	v_perm_b32 v79, v94, v87, s1
	v_perm_b32 v78, v108, v101, s1
	v_perm_b32 v77, v122, v115, s1
	s_waitcnt lgkmcnt(6)
	v_perm_b32 v76, v137, v129, s1
	s_nop 1
	v_mfma_f32_16x16x32_bf16 v[52:55], v[76:79], v[80:83], v[52:55]
	v_perm_b32 v79, v95, v88, s1
	v_perm_b32 v78, v109, v102, s1
	v_perm_b32 v77, v123, v116, s1
	s_waitcnt lgkmcnt(5)
	v_perm_b32 v76, v138, v130, s1
	s_nop 1
	v_mfma_f32_16x16x32_bf16 v[56:59], v[76:79], v[80:83], v[56:59]
	v_perm_b32 v79, v96, v89, s1
	v_perm_b32 v78, v110, v103, s1
	v_perm_b32 v77, v124, v117, s1
	s_waitcnt lgkmcnt(4)
	v_perm_b32 v76, v139, v131, s1
	s_nop 1
	v_mfma_f32_16x16x32_bf16 v[60:63], v[76:79], v[80:83], v[60:63]
	v_perm_b32 v79, v97, v90, s1
	v_perm_b32 v78, v111, v104, s1
	v_perm_b32 v77, v125, v118, s1
	s_waitcnt lgkmcnt(3)
	v_perm_b32 v76, v140, v132, s1
	s_nop 1
	v_mfma_f32_16x16x32_bf16 v[64:67], v[76:79], v[80:83], v[64:67]
	v_perm_b32 v79, v98, v91, s1
	v_perm_b32 v78, v112, v105, s1
	v_perm_b32 v77, v126, v119, s1
	s_waitcnt lgkmcnt(2)
	v_perm_b32 v76, v141, v133, s1
	s_nop 1
	v_mfma_f32_16x16x32_bf16 v[68:71], v[76:79], v[80:83], v[68:71]
	v_perm_b32 v79, v99, v92, s1
	v_perm_b32 v78, v113, v106, s1
	v_perm_b32 v77, v127, v120, s1
	s_waitcnt lgkmcnt(1)
	v_perm_b32 v76, v142, v134, s1
	s_nop 1
	v_mfma_f32_16x16x32_bf16 v[72:75], v[76:79], v[80:83], v[72:75]
	v_perm_b32 v79, v100, v93, s1
	v_perm_b32 v78, v114, v107, s1
	v_perm_b32 v77, v128, v121, s1
	s_waitcnt lgkmcnt(0)
	v_perm_b32 v76, v143, v135, s1
	s_nop 1
	v_mfma_f32_16x16x32_bf16 v[48:51], v[76:79], v[80:83], v[48:51]
	global_store_dwordx4 v[34:35], v[44:47], off offset:-256
	global_store_dwordx4 v[34:35], v[52:55], off offset:-192
	global_store_dwordx4 v[34:35], v[56:59], off offset:-128
	global_store_dwordx4 v[34:35], v[60:63], off offset:-64
	global_store_dwordx4 v[34:35], v[64:67], off
	global_store_dwordx4 v[34:35], v[68:71], off offset:64
	global_store_dwordx4 v[34:35], v[72:75], off offset:128
	s_nop 0
	global_store_dwordx4 v[34:35], v[48:51], off offset:192
	v_lshl_add_u64 v[34:35], v[34:35], 0, s[4:5]
	s_barrier
	s_cbranch_vccz .LBB0_726

.LBB0_1205:
	s_cmp_lt_i32 s84, 12
	s_cselect_b64 s[4:5], -1, 0
	s_and_b64 s[4:5], s[4:5], s[0:1]
	s_andn2_b64 vcc, exec, s[4:5]
	s_cbranch_vccnz .LBB0_1230
	s_cmp_eq_u32 s98, 4
	s_cbranch_scc1 .LBB0_1230
	s_cmpk_gt_i32 s2, 0x5ab
	v_readfirstlane_b32 s12, v175
	s_cbranch_scc1 .LBB0_1230
	s_ashr_i32 s3, s2, 31
	s_lshr_b32 s0, s3, 29
	s_add_i32 s7, s2, s0
	s_and_b32 s0, s7, -8
	s_sub_i32 s8, s2, s0
	s_cmp_gt_i32 s8, 3
	s_cbranch_scc0 .LBB0_1209
	s_mul_i32 s0, s8, 0xb5
	s_add_i32 s6, s0, 4
	s_cbranch_execz .LBB0_1210
	s_branch .LBB0_1211

.LBB0_1211:
	s_waitcnt vmcnt(0)
	v_lshrrev_b32_e32 v2, 1, v175
	v_and_b32_e32 v11, 24, v2
	v_lshrrev_b32_e32 v2, 5, v175
	v_and_b32_e32 v2, 4, v2
	v_bfe_u32 v3, v175, 2, 2
	s_ashr_i32 s0, s7, 3
	v_lshlrev_b32_e32 v0, 4, v175
	v_and_b32_e32 v1, 32, v175
	v_bfe_u32 v10, v175, 2, 4
	v_or3_b32 v2, v2, v3, v11
	v_lshrrev_b32_e32 v3, 3, v175
	s_movk_i32 s7, 0x70
	v_bitop3_b32 v8, v0, v1, 48 bitop3:0x6c
	v_and_b32_e32 v9, 64, v175
	v_and_or_b32 v4, v3, s7, v10
	s_movk_i32 s7, 0x60
	v_add_u32_e32 v12, 0x2000, v0
	v_or_b32_e32 v1, v8, v9
	v_and_or_b32 v3, v3, s7, v2
	v_lshrrev_b32_e32 v0, 7, v12
	s_movk_i32 s7, 0xf0
	s_add_i32 s0, s6, s0
	s_sub_i32 s0, 0x5ab, s0
	v_lshl_or_b32 v130, v3, 11, v1
	v_and_or_b32 v3, v0, s7, v10
	s_movk_i32 s7, 0xe0
	s_mul_hi_i32 s6, s0, 0x2e8ba2e9
	v_and_or_b32 v0, v0, s7, v2
	s_lshr_b32 s7, s6, 31
	s_ashr_i32 s6, s6, 4
	s_add_i32 s6, s6, s7
	s_lshl_b32 s8, s6, 2
	s_sub_i32 s7, 0x42, s8
	s_mulk_i32 s6, 0x58
	s_min_u32 s9, s7, 4
	s_sub_i32 s11, s0, s6
	v_lshl_or_b32 v128, v4, 11, v1
	v_lshl_or_b32 v132, v3, 11, v1
	v_lshl_or_b32 v134, v0, 11, v1
	s_sext_i32_i8 s0, s11
	v_cvt_f32_ubyte0_e32 v1, s9
	v_cvt_f32_i32_e32 v0, s0
	v_rcp_iflag_f32_e32 v2, v1
	s_lshr_b32 s10, s12, 6
	s_ashr_i32 s0, s0, 30
	s_lshr_b32 s1, s12, 8
	v_mul_f32_e32 v2, v0, v2
	v_trunc_f32_e32 v2, v2
	v_fma_f32 v0, -v2, v1, v0
	v_cvt_i32_f32_e32 v2, v2
	s_lshl_b32 s40, s10, 10
	s_or_b32 s0, s0, 1
	v_cmp_ge_f32_e64 s[6:7], |v0|, v1
	s_and_b64 s[6:7], s[6:7], exec
	s_cselect_b32 s0, s0, 0
	v_readfirstlane_b32 s6, v2
	s_add_i32 s0, s6, s0
	s_mul_i32 s6, s0, s9
	s_sub_i32 s6, s11, s6
	s_sext_i32_i8 s6, s6
	s_add_i32 s36, s8, s6
	s_ashr_i32 s37, s36, 31
	s_bfe_i64 s[8:9], s[0:1], 0x80000
	s_lshl_b64 s[6:7], s[36:37], 19
	s_lshl_b64 s[8:9], s[8:9], 19
	s_add_u32 s42, s62, s8
	s_addc_u32 s43, s63, s9
	s_add_i32 s37, s40, 0
	s_add_i32 m0, s37, 0x10000
	v_mov_b32_e32 v131, 0
	global_load_lds_dwordx4 v130, s[42:43]
	s_add_i32 m0, s37, 0x12000
	s_add_u32 s8, s42, 0x40000
	global_load_lds_dwordx4 v134, s[42:43]
	s_addc_u32 s9, s43, 0
	s_add_i32 m0, s37, 0x14000
	v_mov_b32_e32 v135, v131
	global_load_lds_dwordx4 v130, s[8:9]
	s_add_i32 m0, s37, 0x16000
	s_add_u32 s6, s24, s6
	s_addc_u32 s7, s25, s7
	s_add_i32 s41, s37, 0x2000
	global_load_lds_dwordx4 v134, s[8:9]
	s_mov_b32 m0, s37
	s_add_u32 s8, s6, 0x40000
	global_load_lds_dwordx4 v128, s[6:7]
	s_mov_b32 m0, s41
	s_addc_u32 s9, s7, 0
	s_add_i32 s44, s37, 0x4000
	global_load_lds_dwordx4 v132, s[6:7]
	s_mov_b32 m0, s44
	s_add_i32 s45, s37, 0x6000
	global_load_lds_dwordx4 v128, s[8:9]
	s_mov_b32 m0, s45
	v_mov_b32_e32 v129, v131
	global_load_lds_dwordx4 v132, s[8:9]
	v_mov_b32_e32 v133, v131
	s_cmp_eq_u32 s1, 1
	s_mov_b32 s46, 0
	v_lshl_add_u64 v[6:7], s[42:43], 0, v[130:131]
	v_lshl_add_u64 v[4:5], s[42:43], 0, v[134:135]
	v_lshl_add_u64 v[0:1], s[6:7], 0, v[128:129]
	s_cselect_b64 s[8:9], -1, 0
	s_cmp_lg_u32 s1, 1
	v_lshl_add_u64 v[2:3], s[6:7], 0, v[132:133]
	s_cbranch_scc1 .LBB0_1213
	s_barrier

.LBB0_1221:
	s_ashr_i32 s14, s16, 3
	s_add_i32 s14, s20, s14
	s_sub_i32 s14, 0x5ab, s14
	s_mul_hi_i32 s15, s14, 0x2e8ba2e9
	s_lshr_b32 s16, s15, 31
	s_ashr_i32 s15, s15, 4
	s_add_i32 s15, s15, s16
	s_lshl_b32 s16, s15, 2
	s_sub_i32 s17, 0x42, s16
	s_min_i32 s17, s17, 4
	s_abs_i32 s20, s17
	v_cvt_f32_u32_e32 v0, s20
	s_sub_i32 s28, 0, s20
	s_mulk_i32 s15, 0x58
	s_sub_i32 s15, s14, s15
	v_rcp_iflag_f32_e32 v0, v0
	s_abs_i32 s14, s15
	s_xor_b32 s21, s15, s17
	s_ashr_i32 s21, s21, 31
	v_mul_f32_e32 v0, 0x4f7ffffe, v0
	v_cvt_u32_f32_e32 v0, v0
	s_nop 0
	v_readfirstlane_b32 s29, v0
	s_mul_i32 s28, s28, s29
	s_mul_hi_u32 s28, s29, s28
	s_add_i32 s29, s29, s28
	s_mul_hi_u32 s28, s14, s29
	s_mul_i32 s29, s28, s20
	s_sub_i32 s14, s14, s29
	s_add_i32 s30, s28, 1
	s_sub_i32 s29, s14, s20
	s_cmp_ge_u32 s14, s20
	s_cselect_b32 s28, s30, s28
	s_cselect_b32 s14, s29, s14
	s_add_i32 s29, s28, 1
	s_cmp_ge_u32 s14, s20
	s_cselect_b32 s14, s29, s28
	s_xor_b32 s14, s14, s21
	s_sub_i32 s14, s14, s21
	s_mul_i32 s17, s14, s17
	s_sub_i32 s15, s15, s17
	s_add_i32 s16, s16, s15

.LBB0_1226:
	v_mul_f32_e32 v157, 0xbfb8aa3b, v124
	v_exp_f32_e32 v157, v157
	v_mul_f32_e32 v160, 0xbfb8aa3b, v125
	v_exp_f32_e32 v160, v160
	v_lshl_or_b32 v148, s54, 7, v152
	v_add_f32_e32 v157, 1.0, v157
	v_rcp_f32_e32 v157, v157
	v_add_f32_e32 v160, 1.0, v160
	v_rcp_f32_e32 v160, v160
	v_lshl_add_u32 v156, s36, 8, v150
	v_mul_f32_e32 v124, v124, v157
	v_mul_f32_e32 v116, v116, v124
	v_mul_f32_e32 v124, v125, v160
	v_mul_f32_e32 v125, 0xbfb8aa3b, v126
	v_exp_f32_e32 v125, v125
	v_mul_f32_e32 v157, 0xbfb8aa3b, v127
	v_exp_f32_e32 v157, v157
	v_mul_f32_e32 v117, v117, v124
	v_add_f32_e32 v124, 1.0, v125
	v_rcp_f32_e32 v124, v124
	v_add_f32_e32 v125, 1.0, v157
	v_rcp_f32_e32 v125, v125
	v_cvt_pk_bf16_f32 v116, v116, v117
	v_mul_f32_e32 v117, v126, v124
	v_mul_f32_e32 v124, 0xbfb8aa3b, v120
	v_exp_f32_e32 v124, v124
	v_mul_f32_e32 v117, v118, v117
	v_mul_f32_e32 v118, v127, v125
	v_mul_f32_e32 v125, 0xbfb8aa3b, v121
	v_exp_f32_e32 v125, v125
	v_mul_f32_e32 v118, v119, v118
	v_add_f32_e32 v119, 1.0, v124
	v_rcp_f32_e32 v119, v119
	v_add_f32_e32 v124, 1.0, v125
	v_rcp_f32_e32 v124, v124
	v_cvt_pk_bf16_f32 v117, v117, v118
	v_mul_f32_e32 v118, v120, v119
	v_mul_f32_e32 v119, 0xbfb8aa3b, v122
	v_exp_f32_e32 v119, v119
	v_mul_f32_e32 v120, 0xbfb8aa3b, v123
	v_exp_f32_e32 v120, v120
	v_mul_f32_e32 v112, v112, v118
	v_mul_f32_e32 v118, v121, v124
	v_mul_f32_e32 v113, v113, v118
	v_add_f32_e32 v118, 1.0, v119
	v_rcp_f32_e32 v119, v118
	v_add_f32_e32 v118, 1.0, v120
	v_rcp_f32_e32 v120, v118
	v_cvt_pk_bf16_f32 v118, v112, v113
	v_mul_f32_e32 v112, v122, v119
	v_mul_f32_e32 v112, v114, v112
	v_mul_f32_e32 v113, v123, v120
	v_mul_f32_e32 v113, v115, v113
	v_cvt_pk_bf16_f32 v119, v112, v113
	v_mul_f32_e32 v113, 0xbfb8aa3b, v108
	v_exp_f32_e32 v114, v113
	v_mul_f32_e32 v113, 0xbfb8aa3b, v109
	v_exp_f32_e32 v115, v113
	v_ashrrev_i32_e32 v149, 31, v148
	v_add_f32_e32 v114, 1.0, v114
	v_rcp_f32_e32 v114, v114
	v_add_f32_e32 v115, 1.0, v115
	v_rcp_f32_e32 v115, v115
	v_mov_b64_e32 v[146:147], s[18:19]
	v_mul_f32_e32 v108, v108, v114
	v_mul_f32_e32 v100, v100, v108
	v_mul_f32_e32 v108, v109, v115
	v_mul_f32_e32 v109, 0xbfb8aa3b, v110
	v_exp_f32_e32 v109, v109
	v_mul_f32_e32 v114, 0xbfb8aa3b, v111
	v_exp_f32_e32 v114, v114
	v_mul_f32_e32 v101, v101, v108
	v_add_f32_e32 v108, 1.0, v109
	v_rcp_f32_e32 v108, v108
	v_mad_i64_i32 v[158:159], s[6:7], v156, s53, v[146:147]
	v_lshlrev_b64 v[148:149], 1, v[148:149]
	v_lshl_add_u64 v[158:159], v[158:159], 0, v[148:149]
	v_add_f32_e32 v109, 1.0, v114
	global_store_dwordx4 v[158:159], v[116:119], off
	v_rcp_f32_e32 v109, v109
	v_cvt_pk_bf16_f32 v100, v100, v101
	v_mul_f32_e32 v101, v110, v108
	v_mul_f32_e32 v108, 0xbfb8aa3b, v104
	v_exp_f32_e32 v108, v108
	v_mul_f32_e32 v101, v102, v101
	v_mul_f32_e32 v102, v111, v109
	v_mul_f32_e32 v109, 0xbfb8aa3b, v105
	v_exp_f32_e32 v109, v109
	v_mul_f32_e32 v102, v103, v102
	v_add_f32_e32 v103, 1.0, v108
	v_rcp_f32_e32 v103, v103
	v_add_f32_e32 v108, 1.0, v109
	v_rcp_f32_e32 v108, v108
	v_cvt_pk_bf16_f32 v101, v101, v102
	v_mul_f32_e32 v102, v104, v103
	v_mul_f32_e32 v103, 0xbfb8aa3b, v106
	v_exp_f32_e32 v103, v103
	v_mul_f32_e32 v104, 0xbfb8aa3b, v107
	v_exp_f32_e32 v104, v104
	v_mul_f32_e32 v96, v96, v102
	v_mul_f32_e32 v102, v105, v108
	v_mul_f32_e32 v97, v97, v102
	v_add_f32_e32 v102, 1.0, v103
	v_rcp_f32_e32 v103, v102
	v_add_f32_e32 v102, 1.0, v104
	v_rcp_f32_e32 v104, v102
	v_cvt_pk_bf16_f32 v102, v96, v97
	v_mul_f32_e32 v96, v106, v103
	v_mul_f32_e32 v96, v98, v96
	v_mul_f32_e32 v97, v107, v104
	v_mul_f32_e32 v97, v99, v97
	v_cvt_pk_bf16_f32 v103, v96, v97
	v_mul_f32_e32 v97, 0xbfb8aa3b, v92
	v_exp_f32_e32 v98, v97
	v_mul_f32_e32 v97, 0xbfb8aa3b, v93
	v_exp_f32_e32 v99, v97
	v_or_b32_e32 v112, 16, v156
	v_add_f32_e32 v98, 1.0, v98
	v_rcp_f32_e32 v98, v98
	v_add_f32_e32 v99, 1.0, v99
	v_rcp_f32_e32 v99, v99
	v_mad_i64_i32 v[112:113], s[6:7], v112, s53, v[146:147]
	v_mul_f32_e32 v92, v92, v98
	v_mul_f32_e32 v84, v84, v92
	v_mul_f32_e32 v92, v93, v99
	v_mul_f32_e32 v93, 0xbfb8aa3b, v94
	v_exp_f32_e32 v93, v93
	v_mul_f32_e32 v98, 0xbfb8aa3b, v95
	v_exp_f32_e32 v98, v98
	v_mul_f32_e32 v85, v85, v92
	v_add_f32_e32 v92, 1.0, v93
	v_rcp_f32_e32 v92, v92
	v_lshl_add_u64 v[112:113], v[112:113], 0, v[148:149]
	v_add_f32_e32 v93, 1.0, v98
	global_store_dwordx4 v[112:113], v[100:103], off
	v_rcp_f32_e32 v93, v93
	v_cvt_pk_bf16_f32 v84, v84, v85
	v_mul_f32_e32 v85, v94, v92
	v_mul_f32_e32 v92, 0xbfb8aa3b, v88
	v_exp_f32_e32 v92, v92
	v_mul_f32_e32 v85, v86, v85
	v_mul_f32_e32 v86, v95, v93
	v_mul_f32_e32 v93, 0xbfb8aa3b, v89
	v_exp_f32_e32 v93, v93
	v_mul_f32_e32 v86, v87, v86
	v_add_f32_e32 v87, 1.0, v92
	v_rcp_f32_e32 v87, v87
	v_add_f32_e32 v92, 1.0, v93
	v_rcp_f32_e32 v92, v92
	v_cvt_pk_bf16_f32 v85, v85, v86
	v_mul_f32_e32 v86, v88, v87
	v_mul_f32_e32 v87, 0xbfb8aa3b, v90
	v_exp_f32_e32 v87, v87
	v_mul_f32_e32 v88, 0xbfb8aa3b, v91
	v_exp_f32_e32 v88, v88
	v_mul_f32_e32 v80, v80, v86
	v_mul_f32_e32 v86, v89, v92
	v_mul_f32_e32 v81, v81, v86
	v_add_f32_e32 v86, 1.0, v87
	v_rcp_f32_e32 v87, v86
	v_add_f32_e32 v86, 1.0, v88
	v_rcp_f32_e32 v88, v86
	v_cvt_pk_bf16_f32 v86, v80, v81
	v_mul_f32_e32 v80, v90, v87
	v_mul_f32_e32 v80, v82, v80
	v_mul_f32_e32 v81, v91, v88
	v_mul_f32_e32 v81, v83, v81
	v_cvt_pk_bf16_f32 v87, v80, v81
	v_mul_f32_e32 v81, 0xbfb8aa3b, v76
	v_exp_f32_e32 v82, v81
	v_mul_f32_e32 v81, 0xbfb8aa3b, v77
	v_exp_f32_e32 v83, v81
	v_or_b32_e32 v96, 32, v156
	v_add_f32_e32 v82, 1.0, v82
	v_rcp_f32_e32 v82, v82
	v_add_f32_e32 v83, 1.0, v83
	v_rcp_f32_e32 v83, v83
	v_mad_i64_i32 v[96:97], s[6:7], v96, s53, v[146:147]
	v_mul_f32_e32 v76, v76, v82
	v_mul_f32_e32 v68, v68, v76
	v_mul_f32_e32 v76, v77, v83
	v_mul_f32_e32 v77, 0xbfb8aa3b, v78
	v_exp_f32_e32 v77, v77
	v_mul_f32_e32 v82, 0xbfb8aa3b, v79
	v_exp_f32_e32 v82, v82
	v_mul_f32_e32 v69, v69, v76
	v_add_f32_e32 v76, 1.0, v77
	v_rcp_f32_e32 v76, v76
	v_lshl_add_u64 v[96:97], v[96:97], 0, v[148:149]
	v_add_f32_e32 v77, 1.0, v82
	global_store_dwordx4 v[96:97], v[84:87], off
	v_rcp_f32_e32 v77, v77
	v_cvt_pk_bf16_f32 v68, v68, v69
	v_mul_f32_e32 v69, v78, v76
	v_mul_f32_e32 v76, 0xbfb8aa3b, v72
	v_exp_f32_e32 v76, v76
	v_mul_f32_e32 v69, v70, v69
	v_mul_f32_e32 v70, v79, v77
	v_mul_f32_e32 v77, 0xbfb8aa3b, v73
	v_exp_f32_e32 v77, v77
	v_mul_f32_e32 v70, v71, v70
	v_add_f32_e32 v71, 1.0, v76
	v_rcp_f32_e32 v71, v71
	v_add_f32_e32 v76, 1.0, v77
	v_rcp_f32_e32 v76, v76
	v_cvt_pk_bf16_f32 v69, v69, v70
	v_mul_f32_e32 v70, v72, v71
	v_mul_f32_e32 v71, 0xbfb8aa3b, v74
	v_exp_f32_e32 v71, v71
	v_mul_f32_e32 v72, 0xbfb8aa3b, v75
	v_exp_f32_e32 v72, v72
	v_mul_f32_e32 v64, v64, v70
	v_mul_f32_e32 v70, v73, v76
	v_mul_f32_e32 v65, v65, v70
	v_add_f32_e32 v70, 1.0, v71
	v_rcp_f32_e32 v71, v70
	v_add_f32_e32 v70, 1.0, v72
	v_rcp_f32_e32 v72, v70
	v_cvt_pk_bf16_f32 v70, v64, v65
	v_mul_f32_e32 v64, v74, v71
	v_mul_f32_e32 v64, v66, v64
	v_mul_f32_e32 v65, v75, v72
	v_mul_f32_e32 v65, v67, v65
	v_cvt_pk_bf16_f32 v71, v64, v65
	v_mul_f32_e32 v65, 0xbfb8aa3b, v60
	v_exp_f32_e32 v66, v65
	v_mul_f32_e32 v65, 0xbfb8aa3b, v61
	v_exp_f32_e32 v67, v65
	v_or_b32_e32 v80, 48, v156
	v_add_f32_e32 v66, 1.0, v66
	v_rcp_f32_e32 v66, v66
	v_add_f32_e32 v67, 1.0, v67
	v_rcp_f32_e32 v67, v67
	v_mad_i64_i32 v[80:81], s[6:7], v80, s53, v[146:147]
	v_mul_f32_e32 v60, v60, v66
	v_mul_f32_e32 v52, v52, v60
	v_mul_f32_e32 v60, v61, v67
	v_mul_f32_e32 v61, 0xbfb8aa3b, v62
	v_exp_f32_e32 v61, v61
	v_mul_f32_e32 v66, 0xbfb8aa3b, v63
	v_exp_f32_e32 v66, v66
	v_mul_f32_e32 v53, v53, v60
	v_add_f32_e32 v60, 1.0, v61
	v_rcp_f32_e32 v60, v60
	v_lshl_add_u64 v[80:81], v[80:81], 0, v[148:149]
	v_add_f32_e32 v61, 1.0, v66
	global_store_dwordx4 v[80:81], v[68:71], off
	v_rcp_f32_e32 v61, v61
	v_cvt_pk_bf16_f32 v52, v52, v53
	v_mul_f32_e32 v53, v62, v60
	v_mul_f32_e32 v60, 0xbfb8aa3b, v56
	v_exp_f32_e32 v60, v60
	v_mul_f32_e32 v53, v54, v53
	v_mul_f32_e32 v54, v63, v61
	v_mul_f32_e32 v61, 0xbfb8aa3b, v57
	v_exp_f32_e32 v61, v61
	v_mul_f32_e32 v54, v55, v54
	v_add_f32_e32 v55, 1.0, v60
	v_rcp_f32_e32 v55, v55
	v_add_f32_e32 v60, 1.0, v61
	v_rcp_f32_e32 v60, v60
	v_cvt_pk_bf16_f32 v53, v53, v54
	v_mul_f32_e32 v54, v56, v55
	v_mul_f32_e32 v55, 0xbfb8aa3b, v58
	v_exp_f32_e32 v55, v55
	v_mul_f32_e32 v56, 0xbfb8aa3b, v59
	v_exp_f32_e32 v56, v56
	v_mul_f32_e32 v48, v48, v54
	v_mul_f32_e32 v54, v57, v60
	v_mul_f32_e32 v49, v49, v54
	v_add_f32_e32 v54, 1.0, v55
	v_rcp_f32_e32 v55, v54
	v_add_f32_e32 v54, 1.0, v56
	v_rcp_f32_e32 v56, v54
	v_cvt_pk_bf16_f32 v54, v48, v49
	v_mul_f32_e32 v48, v58, v55
	v_mul_f32_e32 v48, v50, v48
	v_mul_f32_e32 v49, v59, v56
	v_mul_f32_e32 v49, v51, v49
	v_cvt_pk_bf16_f32 v55, v48, v49
	v_mul_f32_e32 v49, 0xbfb8aa3b, v44
	v_exp_f32_e32 v50, v49
	v_mul_f32_e32 v49, 0xbfb8aa3b, v45
	v_exp_f32_e32 v51, v49
	v_add_u32_e32 v64, 0x80, v156
	v_add_f32_e32 v50, 1.0, v50
	v_rcp_f32_e32 v50, v50
	v_add_f32_e32 v51, 1.0, v51
	v_rcp_f32_e32 v51, v51
	v_mad_i64_i32 v[64:65], s[6:7], v64, s53, v[146:147]
	v_mul_f32_e32 v44, v44, v50
	v_mul_f32_e32 v36, v36, v44
	v_mul_f32_e32 v44, v45, v51
	v_mul_f32_e32 v45, 0xbfb8aa3b, v46
	v_exp_f32_e32 v45, v45
	v_mul_f32_e32 v50, 0xbfb8aa3b, v47
	v_exp_f32_e32 v50, v50
	v_mul_f32_e32 v37, v37, v44
	v_add_f32_e32 v44, 1.0, v45
	v_rcp_f32_e32 v44, v44
	v_lshl_add_u64 v[64:65], v[64:65], 0, v[148:149]
	v_add_f32_e32 v45, 1.0, v50
	global_store_dwordx4 v[64:65], v[52:55], off
	v_rcp_f32_e32 v45, v45
	v_cvt_pk_bf16_f32 v36, v36, v37
	v_mul_f32_e32 v37, v46, v44
	v_mul_f32_e32 v44, 0xbfb8aa3b, v40
	v_exp_f32_e32 v44, v44
	v_mul_f32_e32 v37, v38, v37
	v_mul_f32_e32 v38, v47, v45
	v_mul_f32_e32 v45, 0xbfb8aa3b, v41
	v_exp_f32_e32 v45, v45
	v_mul_f32_e32 v38, v39, v38
	v_add_f32_e32 v39, 1.0, v44
	v_rcp_f32_e32 v39, v39
	v_add_f32_e32 v44, 1.0, v45
	v_rcp_f32_e32 v44, v44
	v_cvt_pk_bf16_f32 v37, v37, v38
	v_mul_f32_e32 v38, v40, v39
	v_mul_f32_e32 v39, 0xbfb8aa3b, v42
	v_exp_f32_e32 v39, v39
	v_mul_f32_e32 v40, 0xbfb8aa3b, v43
	v_exp_f32_e32 v40, v40
	v_mul_f32_e32 v32, v32, v38
	v_mul_f32_e32 v38, v41, v44
	v_mul_f32_e32 v33, v33, v38
	v_add_f32_e32 v38, 1.0, v39
	v_rcp_f32_e32 v39, v38
	v_add_f32_e32 v38, 1.0, v40
	v_rcp_f32_e32 v40, v38
	v_cvt_pk_bf16_f32 v38, v32, v33
	v_mul_f32_e32 v32, v42, v39
	v_mul_f32_e32 v32, v34, v32
	v_mul_f32_e32 v33, v43, v40
	v_mul_f32_e32 v33, v35, v33
	v_cvt_pk_bf16_f32 v39, v32, v33
	v_mul_f32_e32 v33, 0xbfb8aa3b, v28
	v_exp_f32_e32 v34, v33
	v_mul_f32_e32 v33, 0xbfb8aa3b, v29
	v_exp_f32_e32 v35, v33
	v_add_u32_e32 v48, 0x90, v156
	v_add_f32_e32 v34, 1.0, v34
	v_rcp_f32_e32 v34, v34
	v_add_f32_e32 v35, 1.0, v35
	v_rcp_f32_e32 v35, v35
	v_mad_i64_i32 v[48:49], s[6:7], v48, s53, v[146:147]
	v_mul_f32_e32 v28, v28, v34
	v_mul_f32_e32 v20, v20, v28
	v_mul_f32_e32 v28, v29, v35
	v_mul_f32_e32 v29, 0xbfb8aa3b, v30
	v_exp_f32_e32 v29, v29
	v_mul_f32_e32 v34, 0xbfb8aa3b, v31
	v_exp_f32_e32 v34, v34
	v_mul_f32_e32 v21, v21, v28
	v_add_f32_e32 v28, 1.0, v29
	v_rcp_f32_e32 v28, v28
	v_lshl_add_u64 v[48:49], v[48:49], 0, v[148:149]
	v_add_f32_e32 v29, 1.0, v34
	global_store_dwordx4 v[48:49], v[36:39], off
	v_rcp_f32_e32 v29, v29
	v_cvt_pk_bf16_f32 v20, v20, v21
	v_mul_f32_e32 v21, v30, v28
	v_mul_f32_e32 v28, 0xbfb8aa3b, v24
	v_exp_f32_e32 v28, v28
	v_mul_f32_e32 v21, v22, v21
	v_mul_f32_e32 v22, v31, v29
	v_mul_f32_e32 v29, 0xbfb8aa3b, v25
	v_exp_f32_e32 v29, v29
	v_mul_f32_e32 v22, v23, v22
	v_add_f32_e32 v23, 1.0, v28
	v_rcp_f32_e32 v23, v23
	v_add_f32_e32 v28, 1.0, v29
	v_rcp_f32_e32 v28, v28
	v_cvt_pk_bf16_f32 v21, v21, v22
	v_mul_f32_e32 v22, v24, v23
	v_mul_f32_e32 v23, 0xbfb8aa3b, v26
	v_exp_f32_e32 v23, v23
	v_mul_f32_e32 v24, 0xbfb8aa3b, v27
	v_exp_f32_e32 v24, v24
	v_mul_f32_e32 v16, v16, v22
	v_mul_f32_e32 v22, v25, v28
	v_mul_f32_e32 v17, v17, v22
	v_add_f32_e32 v22, 1.0, v23
	v_rcp_f32_e32 v23, v22
	v_add_f32_e32 v22, 1.0, v24
	v_rcp_f32_e32 v24, v22
	v_cvt_pk_bf16_f32 v22, v16, v17
	v_mul_f32_e32 v16, v26, v23
	v_mul_f32_e32 v16, v18, v16
	v_mul_f32_e32 v17, v27, v24
	v_mul_f32_e32 v17, v19, v17
	v_cvt_pk_bf16_f32 v23, v16, v17
	v_mul_f32_e32 v17, 0xbfb8aa3b, v12
	v_exp_f32_e32 v18, v17
	v_mul_f32_e32 v17, 0xbfb8aa3b, v13
	v_exp_f32_e32 v19, v17
	v_add_u32_e32 v32, 0xa0, v156
	v_add_f32_e32 v18, 1.0, v18
	v_rcp_f32_e32 v18, v18
	v_add_f32_e32 v19, 1.0, v19
	v_rcp_f32_e32 v19, v19
	v_mad_i64_i32 v[32:33], s[6:7], v32, s53, v[146:147]
	v_mul_f32_e32 v12, v12, v18
	v_mul_f32_e32 v4, v4, v12
	v_mul_f32_e32 v12, v13, v19
	v_mul_f32_e32 v13, 0xbfb8aa3b, v14
	v_exp_f32_e32 v13, v13
	v_mul_f32_e32 v18, 0xbfb8aa3b, v15
	v_exp_f32_e32 v18, v18
	v_mul_f32_e32 v5, v5, v12
	v_add_f32_e32 v12, 1.0, v13
	v_rcp_f32_e32 v12, v12
	v_lshl_add_u64 v[32:33], v[32:33], 0, v[148:149]
	v_add_f32_e32 v13, 1.0, v18
	global_store_dwordx4 v[32:33], v[20:23], off
	v_rcp_f32_e32 v13, v13
	v_cvt_pk_bf16_f32 v4, v4, v5
	v_mul_f32_e32 v5, v14, v12
	v_mul_f32_e32 v12, 0xbfb8aa3b, v8
	v_exp_f32_e32 v12, v12
	v_mul_f32_e32 v5, v6, v5
	v_mul_f32_e32 v6, v15, v13
	v_mul_f32_e32 v13, 0xbfb8aa3b, v9
	v_exp_f32_e32 v13, v13
	v_mul_f32_e32 v6, v7, v6
	v_add_f32_e32 v7, 1.0, v12
	v_rcp_f32_e32 v7, v7
	v_add_f32_e32 v12, 1.0, v13
	v_rcp_f32_e32 v12, v12
	v_cvt_pk_bf16_f32 v5, v5, v6
	v_mul_f32_e32 v6, v8, v7
	v_mul_f32_e32 v7, 0xbfb8aa3b, v10
	v_exp_f32_e32 v7, v7
	v_mul_f32_e32 v8, 0xbfb8aa3b, v11
	v_exp_f32_e32 v8, v8
	v_mul_f32_e32 v0, v0, v6
	v_mul_f32_e32 v6, v9, v12
	v_mul_f32_e32 v1, v1, v6
	v_add_f32_e32 v6, 1.0, v7
	v_rcp_f32_e32 v7, v6
	v_add_f32_e32 v6, 1.0, v8
	v_rcp_f32_e32 v8, v6
	v_add_u32_e32 v16, 0xb0, v156
	v_mad_i64_i32 v[16:17], s[6:7], v16, s53, v[146:147]
	v_lshl_add_u64 v[16:17], v[16:17], 0, v[148:149]
	v_cvt_pk_bf16_f32 v6, v0, v1
	v_mul_f32_e32 v0, v10, v7
	v_mul_f32_e32 v1, v11, v8
	s_andn2_b64 vcc, exec, s[0:1]
	s_mov_b64 s[0:1], -1
	v_mul_f32_e32 v0, v2, v0
	v_mul_f32_e32 v1, v3, v1
	v_cvt_pk_bf16_f32 v7, v0, v1
	global_store_dwordx4 v[16:17], v[4:7], off
	s_cmp_lt_i32 s36, 64
	s_cbranch_scc1 .Lsg11_skip
	s_waitcnt vmcnt(0)
	s_mov_b64 exec, 1
	s_lshl_b32 s99, s2, 2
	v_mov_b32_e32 v0, 0x4c00
	v_add_u32_e32 v0, s99, v0
	v_mov_b32_e32 v1, 1
	global_atomic_add v2, v0, v1, s[94:95] sc0
	s_waitcnt vmcnt(0)
	v_readfirstlane_b32 s99, v2
	s_nop 1
	s_and_b32 s99, s99, 7
	s_cmp_lg_u32 s99, 7
	s_cbranch_scc1 .Lsg11_done
	buffer_wbl2 sc1
	s_waitcnt vmcnt(0)
	v_mov_b32_e32 v0, 0x4a00
	global_atomic_add v0, v1, s[94:95]

.Lsg11_skip:
	s_cbranch_vccnz .LBB0_1215
	s_andn2_b64 vcc, exec, s[8:9]
	s_cbranch_vccnz .LBB0_1214
	s_barrier
	s_branch .LBB0_1214

.LBB0_1230:
	s_cmp_gt_i32 s85, 12
	s_cselect_b64 s[0:1], -1, 0
	s_and_b64 s[4:5], s[4:5], s[0:1]
	s_andn2_b64 vcc, exec, s[4:5]
	s_cbranch_vccnz .LBB0_1282
	s_cmp_gt_u32 s98, 2
	s_cbranch_scc1 .Ltg11_no
	s_bitcmp1_b32 s98, 0
	s_cbranch_scc1 .Ltg11_no
	s_cmp_lt_u32 s2, 172
	s_cbranch_scc1 .Ltg11_no
	s_cmp_gt_u32 s2, 251
	s_cbranch_scc1 .Ltg11_no
	s_mov_b32 s98, 3
	s_mov_b64 exec, -1
	s_mov_b64 s[0:1], s[100:101]
	v_readlane_b32 s99, v255, 63
	v_mbcnt_lo_u32_b32 v0, -1, 0
	v_mbcnt_hi_u32_b32 v0, -1, v0
	s_nop 1
	v_add_u32_e32 v0, s99, v0
	s_branch .Lp_tramp
.Ltg11_no:
	s_waitcnt vmcnt(0)
	s_waitcnt vmcnt(0)
	s_barrier
	s_mov_b64 s[4:5], exec
	v_readlane_b32 s6, v254, 4
	v_readlane_b32 s7, v254, 5
	s_and_b64 s[6:7], s[4:5], s[6:7]
	s_mov_b64 exec, s[6:7]
	s_cbranch_execz .LBB0_1281
	s_add_i32 s3, 0, 0x20020
	v_mov_b32_e32 v0, s3
	s_waitcnt vmcnt(0) expcnt(0) lgkmcnt(0)
	ds_read_b32 v2, v0
	s_add_i32 s3, 0, 0x20024
	v_mov_b32_e32 v0, s3
	ds_read_b32 v0, v0
	s_waitcnt lgkmcnt(1)
	v_cmp_ne_u32_e32 vcc, 0, v2
	s_cbranch_vccnz .LBB0_1247
	s_add_u32 s6, s94, 0x1200
	s_addc_u32 s7, s95, 0
	s_add_u32 s8, s94, 0x1400
	s_addc_u32 s9, s95, 0
	s_add_u32 s10, s94, 0x1500
	s_addc_u32 s11, s95, 0
	s_add_u32 s12, s94, 0x1600
	s_addc_u32 s13, s95, 0
	s_add_u32 s14, s94, 0x1700
	s_addc_u32 s15, s95, 0
	s_add_u32 s16, s94, 0x1800
	s_addc_u32 s17, s95, 0
	s_add_u32 s20, s94, 0x1900
	s_addc_u32 s21, s95, 0
	s_add_u32 s24, s94, 0x1a00
	s_addc_u32 s25, s95, 0
	s_add_u32 s28, s94, 0x1b00
	s_addc_u32 s29, s95, 0
	s_add_u32 s30, s94, 0x1c00
	s_addc_u32 s31, s95, 0
	s_add_u32 s36, s94, 0x1d00
	s_addc_u32 s37, s95, 0
	s_add_u32 s38, s94, 0x1e00
	s_addc_u32 s39, s95, 0
	s_add_u32 s40, s94, 0x1f00
	s_addc_u32 s41, s95, 0
	s_add_u32 s42, s94, 0x2000
	s_addc_u32 s43, s95, 0
	s_add_u32 s44, s94, 0x2100
	s_addc_u32 s45, s95, 0
	s_add_u32 s46, s94, 0x2200
	s_addc_u32 s47, s95, 0
	s_mul_i32 s3, s35, s75
	s_add_u32 s48, s94, 0x2300
	s_mul_i32 s3, s3, s34
	s_addc_u32 s49, s95, 0
	s_mov_b32 s56, 1
	v_mov_b32_e32 v16, 0
	s_branch .LBB0_1235

.LBB0_1282:
	s_cmp_lt_i32 s84, 13
	s_cselect_b64 s[4:5], -1, 0
	s_and_b64 s[0:1], s[4:5], s[0:1]
	s_andn2_b64 vcc, exec, s[0:1]
	s_cbranch_vccnz .LBB0_1334
	s_cmpk_lg_i32 s34, 0x100
	s_cselect_b64 s[4:5], -1, 0
	s_cmpk_gt_i32 s2, 0x57
	s_cselect_b64 s[6:7], -1, 0
	s_mov_b64 s[8:9], -1
	v_readfirstlane_b32 s16, v175
	s_and_b64 vcc, exec, s[8:9]
	s_cbranch_vccz .LBB0_1286
	s_cmpk_gt_i32 s2, 0xff
	s_mov_b64 s[10:11], 0
	s_cbranch_scc0 .LBB0_1287
	s_add_u32 s4, s2, 0xffffff00
	s_addc_u32 s5, 0, -1
	s_waitcnt vmcnt(0)
	v_mov_b64_e32 v[0:1], 0x58
	v_cmp_lt_u64_e64 s[6:7], s[4:5], v[0:1]
	s_mov_b64 s[12:13], 0
	s_andn2_b64 vcc, exec, s[12:13]
	s_cbranch_vccnz .LBB0_1293
	s_branch .LBB0_1288

.LBB0_1298:
	s_cmp_lg_u32 s98, 3
	s_cbranch_scc1 .Ltl12_go
	s_mov_b32 s99, 0
	v_mov_b32_e32 v0, 0x4a00
.Ltl12_spin:
	global_load_dword v1, v0, s[94:95] sc1
	s_waitcnt vmcnt(0)
	v_readfirstlane_b32 s3, v1
	s_cmp_ge_u32 s3, 88
	s_cbranch_scc1 .Ltl12_rdy
	s_sleep 8
	s_add_u32 s99, s99, 1
	s_cmp_lt_u32 s99, 0x800
	s_cbranch_scc1 .Ltl12_spin
.Ltl12_rdy:
	s_sub_u32 s3, s2, 172
	s_mul_i32 s4, s3, 205
	s_lshr_b32 s4, s4, 11
	s_mul_i32 s5, s4, 10
	s_sub_u32 s36, s3, s5
	s_lshr_b32 s5, s4, 2
	s_add_u32 s64, s5, 64
	s_and_b32 s37, s4, 3
	s_min_u32 s5, s36, 2
	s_lshl_b32 s3, s36, 1
	s_add_u32 s3, s3, s5
	s_lshl_b32 s6, s3, 8
	s_mov_b32 s7, 0
	s_cmp_lt_u32 s36, 2
	s_cselect_b32 s65, 6, 4

.LBB0_1303:
	s_add_i32 s59, s21, 1
	s_mov_b64 s[4:5], -1
	s_and_b64 vcc, exec, s[8:9]
	s_cbranch_vccz .LBB0_1314
	s_mul_i32 s4, s59, s51
	s_mul_hi_u32 s5, s59, s52
	s_add_i32 s5, s5, s4
	s_mul_i32 s4, s59, s52
	s_add_u32 s4, s4, s2
	s_addc_u32 s5, s5, s53
	v_cmp_gt_i64_e32 vcc, s[4:5], v[140:141]
	s_mov_b64 s[24:25], -1
	s_and_b64 vcc, exec, vcc
	s_cbranch_vccz .LBB0_1307
	s_add_u32 s6, s4, 0xffffff00
	s_addc_u32 s7, s5, -1
	v_cmp_gt_u64_e32 vcc, s[6:7], v[142:143]
	s_mov_b64 s[24:25], 0
	s_and_b64 vcc, exec, vcc
	s_mov_b64 s[6:7], 0
	s_mov_b32 s60, s68
	s_mov_b32 s61, s67
	s_mov_b32 s20, s29
	s_mov_b32 s62, s28
	s_mov_b32 s63, s66
	s_branch .LBB0_1307
	s_and_b32 s5, s4, 0xff
	s_mulk_i32 s5, 0x75
	s_lshr_b32 s5, s5, 8
	s_sub_i32 s6, s4, s5
	s_bfe_u32 s6, s6, 0x70001
	s_add_i32 s6, s6, s5
	s_bfe_u32 s7, s6, 0x50003
	s_mul_i32 s7, s7, 11
	s_sub_i32 s7, s4, s7
	s_and_b32 s5, s6, 0xff
	s_and_b32 s63, s7, 0xff
	s_bfe_u32 s6, s6, 0x30005
	s_or_b32 s60, s6, 64
	s_bfe_u32 s61, s5, 0x20003
	s_lshl_b32 s20, s63, 8
	s_mov_b32 s62, 4
	s_mov_b64 s[6:7], -1

.LBB0_1396:
	v_lshl_add_u64 v[22:23], v[16:17], 0, v[48:49]
	v_add_co_u32_e64 v108, s[0:1], s3, v22
	v_add_co_u32_e32 v224, vcc, 0xe600000, v22
	s_nop 0
	v_addc_co_u32_e64 v109, s[0:1], 0, v23, s[0:1]
	v_add_co_u32_e64 v110, s[0:1], s8, v22
	v_lshl_add_u64 v[20:21], v[18:19], 0, v[48:49]
	s_nop 0
	v_addc_co_u32_e64 v111, s[0:1], 0, v23, s[0:1]
	v_add_co_u32_e64 v112, s[0:1], s9, v22
	v_addc_co_u32_e32 v225, vcc, 0, v23, vcc
	s_nop 0
	v_addc_co_u32_e64 v113, s[0:1], 0, v23, s[0:1]
	v_add_co_u32_e64 v114, s[0:1], s10, v22
	global_load_dwordx4 v[32:35], v[20:21], off
	global_load_dwordx4 v[36:39], v[20:21], off offset:1024
	global_load_dwordx4 v[40:43], v[20:21], off offset:2048
	global_load_dwordx4 v[44:47], v[20:21], off offset:3072
	v_addc_co_u32_e64 v115, s[0:1], 0, v23, s[0:1]
	v_add_co_u32_e64 v128, s[0:1], s11, v22
	v_add_u32_e32 v50, s2, v50
	s_nop 0
	v_addc_co_u32_e64 v129, s[0:1], 0, v23, s[0:1]
	v_add_co_u32_e64 v144, s[0:1], s12, v22
	v_lshl_add_u64 v[16:17], v[16:17], 0, s[4:5]
	s_nop 0
	v_addc_co_u32_e64 v145, s[0:1], 0, v23, s[0:1]
	v_add_co_u32_e64 v160, s[0:1], s13, v22
	v_lshl_add_u64 v[18:19], v[18:19], 0, s[4:5]
	s_nop 0
	v_addc_co_u32_e64 v161, s[0:1], 0, v23, s[0:1]
	v_add_co_u32_e64 v176, s[0:1], s14, v22
	s_nop 1
	v_addc_co_u32_e64 v177, s[0:1], 0, v23, s[0:1]
	v_add_co_u32_e64 v192, s[0:1], s15, v22
	s_nop 1
	v_addc_co_u32_e64 v193, s[0:1], 0, v23, s[0:1]
	v_add_co_u32_e64 v208, s[0:1], s16, v22
	s_nop 1
	v_addc_co_u32_e64 v209, s[0:1], 0, v23, s[0:1]
	global_load_dwordx4 v[52:55], v[108:109], off
	global_load_dwordx4 v[56:59], v[108:109], off offset:1024
	global_load_dwordx4 v[60:63], v[108:109], off offset:2048
	global_load_dwordx4 v[64:67], v[108:109], off offset:3072
	global_load_dwordx4 v[68:71], v[110:111], off
	global_load_dwordx4 v[72:75], v[110:111], off offset:1024
	global_load_dwordx4 v[76:79], v[110:111], off offset:2048
	global_load_dwordx4 v[80:83], v[110:111], off offset:3072
	global_load_dwordx4 v[84:87], v[112:113], off
	global_load_dwordx4 v[88:91], v[112:113], off offset:1024
	global_load_dwordx4 v[92:95], v[112:113], off offset:2048
	global_load_dwordx4 v[96:99], v[112:113], off offset:3072
	global_load_dwordx4 v[100:103], v[114:115], off
	global_load_dwordx4 v[104:107], v[114:115], off offset:1024
	global_load_dwordx4 v[108:111], v[114:115], off offset:2048
	s_nop 0
	global_load_dwordx4 v[112:115], v[114:115], off offset:3072
	s_nop 0
	global_load_dwordx4 v[116:119], v[128:129], off
	global_load_dwordx4 v[120:123], v[128:129], off offset:1024
	global_load_dwordx4 v[124:127], v[128:129], off offset:2048
	s_nop 0
	global_load_dwordx4 v[128:131], v[128:129], off offset:3072
	s_nop 0
	global_load_dwordx4 v[132:135], v[144:145], off
	global_load_dwordx4 v[136:139], v[144:145], off offset:1024
	global_load_dwordx4 v[140:143], v[144:145], off offset:2048
	s_nop 0
	global_load_dwordx4 v[144:147], v[144:145], off offset:3072
	s_nop 0
	global_load_dwordx4 v[148:151], v[160:161], off
	global_load_dwordx4 v[152:155], v[160:161], off offset:1024
	global_load_dwordx4 v[156:159], v[160:161], off offset:2048
	s_nop 0
	global_load_dwordx4 v[160:163], v[160:161], off offset:3072
	s_nop 0
	global_load_dwordx4 v[164:167], v[176:177], off
	global_load_dwordx4 v[168:171], v[176:177], off offset:1024
	global_load_dwordx4 v[172:175], v[176:177], off offset:2048
	s_nop 0
	global_load_dwordx4 v[176:179], v[176:177], off offset:3072
	s_nop 0
	global_load_dwordx4 v[180:183], v[192:193], off
	global_load_dwordx4 v[184:187], v[192:193], off offset:1024
	global_load_dwordx4 v[188:191], v[192:193], off offset:2048
	s_nop 0
	global_load_dwordx4 v[192:195], v[192:193], off offset:3072
	s_nop 0
	s_nop 0
	s_nop 0
	global_load_dwordx4 v[212:215], v[224:225], off
	global_load_dwordx4 v[216:219], v[224:225], off offset:1024
	global_load_dwordx4 v[220:223], v[224:225], off offset:2048
	s_nop 0
	global_load_dwordx4 v[224:227], v[224:225], off offset:3072
	v_cmp_lt_i32_e64 s[0:1], s17, v50
	s_or_b64 s[6:7], s[0:1], s[6:7]
	s_waitcnt vmcnt(3)
	v_pk_add_f32 v[22:23], v[34:35], v[214:215]
	v_pk_add_f32 v[32:33], v[32:33], v[212:213]
	s_waitcnt vmcnt(2)
	v_pk_add_f32 v[34:35], v[38:39], v[218:219]
	v_pk_add_f32 v[36:37], v[36:37], v[216:217]
	v_pk_add_f32 v[22:23], v[22:23], v[54:55]
	v_pk_add_f32 v[32:33], v[32:33], v[52:53]
	v_pk_add_f32 v[34:35], v[34:35], v[58:59]
	v_pk_add_f32 v[36:37], v[36:37], v[56:57]
	s_waitcnt vmcnt(1)
	v_pk_add_f32 v[38:39], v[42:43], v[222:223]
	v_pk_add_f32 v[40:41], v[40:41], v[220:221]
	s_waitcnt vmcnt(0)
	v_pk_add_f32 v[44:45], v[44:45], v[224:225]
	v_pk_add_f32 v[22:23], v[22:23], v[70:71]
	v_pk_add_f32 v[32:33], v[32:33], v[68:69]
	v_pk_add_f32 v[34:35], v[34:35], v[74:75]
	v_pk_add_f32 v[36:37], v[36:37], v[72:73]
	v_pk_add_f32 v[42:43], v[46:47], v[226:227]
	v_pk_add_f32 v[38:39], v[38:39], v[62:63]
	v_pk_add_f32 v[40:41], v[40:41], v[60:61]
	v_pk_add_f32 v[44:45], v[44:45], v[64:65]
	v_pk_add_f32 v[22:23], v[22:23], v[86:87]
	v_pk_add_f32 v[32:33], v[32:33], v[84:85]
	v_pk_add_f32 v[34:35], v[34:35], v[90:91]
	v_pk_add_f32 v[36:37], v[36:37], v[88:89]
	v_pk_add_f32 v[42:43], v[42:43], v[66:67]
	v_pk_add_f32 v[38:39], v[38:39], v[78:79]
	v_pk_add_f32 v[40:41], v[40:41], v[76:77]
	v_pk_add_f32 v[44:45], v[44:45], v[80:81]
	v_pk_add_f32 v[22:23], v[22:23], v[102:103]
	v_pk_add_f32 v[32:33], v[32:33], v[100:101]
	v_pk_add_f32 v[34:35], v[34:35], v[106:107]
	v_pk_add_f32 v[36:37], v[36:37], v[104:105]
	v_pk_add_f32 v[42:43], v[42:43], v[82:83]
	v_pk_add_f32 v[38:39], v[38:39], v[94:95]
	v_pk_add_f32 v[40:41], v[40:41], v[92:93]
	v_pk_add_f32 v[44:45], v[44:45], v[96:97]
	v_pk_add_f32 v[22:23], v[22:23], v[118:119]
	v_pk_add_f32 v[32:33], v[32:33], v[116:117]
	v_pk_add_f32 v[34:35], v[34:35], v[122:123]
	v_pk_add_f32 v[36:37], v[36:37], v[120:121]
	v_pk_add_f32 v[42:43], v[42:43], v[98:99]
	v_pk_add_f32 v[38:39], v[38:39], v[110:111]
	v_pk_add_f32 v[40:41], v[40:41], v[108:109]
	v_pk_add_f32 v[44:45], v[44:45], v[112:113]
	v_pk_add_f32 v[22:23], v[22:23], v[134:135]
	v_pk_add_f32 v[32:33], v[32:33], v[132:133]
	v_pk_add_f32 v[34:35], v[34:35], v[138:139]
	v_pk_add_f32 v[36:37], v[36:37], v[136:137]
	v_pk_add_f32 v[42:43], v[42:43], v[114:115]
	v_pk_add_f32 v[38:39], v[38:39], v[126:127]
	v_pk_add_f32 v[40:41], v[40:41], v[124:125]
	v_pk_add_f32 v[44:45], v[44:45], v[128:129]
	v_pk_add_f32 v[22:23], v[22:23], v[150:151]
	v_pk_add_f32 v[32:33], v[32:33], v[148:149]
	v_pk_add_f32 v[34:35], v[34:35], v[154:155]
	v_pk_add_f32 v[36:37], v[36:37], v[152:153]
	v_pk_add_f32 v[42:43], v[42:43], v[130:131]
	v_pk_add_f32 v[38:39], v[38:39], v[142:143]
	v_pk_add_f32 v[40:41], v[40:41], v[140:141]
	v_pk_add_f32 v[44:45], v[44:45], v[144:145]
	v_pk_add_f32 v[22:23], v[22:23], v[166:167]
	v_pk_add_f32 v[32:33], v[32:33], v[164:165]
	v_pk_add_f32 v[34:35], v[34:35], v[170:171]
	v_pk_add_f32 v[36:37], v[36:37], v[168:169]
	v_pk_add_f32 v[42:43], v[42:43], v[146:147]
	v_pk_add_f32 v[38:39], v[38:39], v[158:159]
	v_pk_add_f32 v[40:41], v[40:41], v[156:157]
	v_pk_add_f32 v[44:45], v[44:45], v[160:161]
	v_pk_add_f32 v[22:23], v[22:23], v[182:183]
	v_pk_add_f32 v[32:33], v[32:33], v[180:181]
	v_pk_add_f32 v[34:35], v[34:35], v[186:187]
	v_pk_add_f32 v[36:37], v[36:37], v[184:185]
	v_pk_add_f32 v[42:43], v[42:43], v[162:163]
	v_pk_add_f32 v[38:39], v[38:39], v[174:175]
	v_pk_add_f32 v[40:41], v[40:41], v[172:173]
	v_pk_add_f32 v[44:45], v[44:45], v[176:177]
	v_pk_add_f32 v[42:43], v[42:43], v[178:179]
	v_pk_add_f32 v[38:39], v[38:39], v[190:191]
	v_pk_add_f32 v[40:41], v[40:41], v[188:189]
	v_pk_add_f32 v[44:45], v[44:45], v[192:193]
	v_pk_mul_f32 v[46:47], v[22:23], v[22:23]
	v_pk_mul_f32 v[52:53], v[32:33], v[32:33]
	v_pk_mul_f32 v[54:55], v[34:35], v[34:35]
	v_pk_mul_f32 v[56:57], v[36:37], v[36:37]
	v_pk_add_f32 v[42:43], v[42:43], v[194:195]
	v_pk_mov_b32 v[62:63], v[52:53], v[46:47] op_sel:[1,0]
	v_mov_b32_e32 v53, v47
	v_pk_mov_b32 v[46:47], v[56:57], v[54:55] op_sel:[1,0]
	v_mov_b32_e32 v57, v55
	v_mul_f32_e32 v61, v45, v45
	v_mul_f32_e32 v58, v41, v41
	v_mul_f32_e32 v60, v39, v39
	v_pk_add_f32 v[52:53], v[62:63], v[52:53]
	v_pk_add_f32 v[46:47], v[46:47], v[56:57]
	v_mul_f32_e32 v51, v44, v44
	v_mul_f32_e32 v64, v42, v42
	v_mul_f32_e32 v65, v43, v43
	v_pk_fma_f32 v[54:55], v[40:41], v[40:41], v[58:59] op_sel_hi:[1,1,0]
	v_pk_fma_f32 v[58:59], v[38:39], v[38:39], v[60:61] op_sel_hi:[1,1,0]
	v_pk_add_f32 v[52:53], v[52:53], v[52:53] op_sel:[0,1] op_sel_hi:[1,0]
	v_pk_add_f32 v[46:47], v[46:47], v[46:47] op_sel:[0,1] op_sel_hi:[1,0]
	v_mov_b32_e32 v55, v64
	v_mov_b32_e32 v59, v65
	v_mov_b32_e32 v53, v51
	v_mov_b32_e32 v47, v61
	v_pk_add_f32 v[54:55], v[54:55], v[58:59]
	v_pk_add_f32 v[46:47], v[52:53], v[46:47]
	s_nop 0
	v_pk_add_f32 v[46:47], v[46:47], v[54:55]
	s_nop 0
	v_add_f32_e32 v46, v46, v47
	ds_bpermute_b32 v47, v24, v46
	s_waitcnt lgkmcnt(0)
	v_add_f32_e32 v46, v46, v47
	ds_bpermute_b32 v47, v25, v46
	s_waitcnt lgkmcnt(0)
	v_add_f32_e32 v46, v46, v47
	ds_bpermute_b32 v47, v26, v46
	s_waitcnt lgkmcnt(0)
	v_add_f32_e32 v46, v46, v47
	ds_bpermute_b32 v47, v27, v46
	s_waitcnt lgkmcnt(0)
	v_add_f32_e32 v46, v46, v47
	ds_bpermute_b32 v47, v28, v46
	s_waitcnt lgkmcnt(0)
	v_add_f32_e32 v46, v46, v47
	ds_bpermute_b32 v47, v29, v46
	s_waitcnt lgkmcnt(0)
	v_add_f32_e32 v46, v46, v47
	v_fmamk_f32 v46, v46, 0x3a800000, v30
	v_mul_f32_e32 v47, 0x4f800000, v46
	v_cmp_gt_f32_e32 vcc, s15, v46
	s_nop 1
	v_cndmask_b32_e32 v46, v46, v47, vcc
	v_sqrt_f32_e32 v47, v46
	s_nop 0
	v_add_u32_e32 v51, -1, v47
	v_add_u32_e32 v52, 1, v47
	v_fma_f32 v53, -v51, v47, v46
	v_fma_f32 v54, -v52, v47, v46
	v_cmp_ge_f32_e64 s[0:1], 0, v53
	s_nop 1
	v_cndmask_b32_e64 v47, v47, v51, s[0:1]
	v_cmp_lt_f32_e64 s[0:1], 0, v54
	s_nop 1
	v_cndmask_b32_e64 v47, v47, v52, s[0:1]
	v_mul_f32_e32 v51, 0x37800000, v47
	v_cndmask_b32_e32 v47, v47, v51, vcc
	v_cmp_class_f32_e32 vcc, v46, v31
	s_nop 1
	v_cndmask_b32_e32 v46, v47, v46, vcc
	v_div_scale_f32 v47, s[0:1], v46, v46, 1.0
	v_rcp_f32_e32 v52, v47
	v_div_scale_f32 v51, vcc, 1.0, v46, 1.0
	v_fma_f32 v53, -v47, v52, 1.0
	v_fmac_f32_e32 v52, v53, v52
	v_mul_f32_e32 v53, v51, v52
	v_fma_f32 v54, -v47, v53, v51
	v_fmac_f32_e32 v53, v54, v52
	v_fma_f32 v47, -v47, v53, v51
	v_div_fmas_f32 v47, v47, v52, v53
	v_div_fixup_f32 v46, v47, v46, 1.0
	v_pk_mul_f32 v[32:33], v[32:33], v[46:47] op_sel_hi:[1,0]
	v_pk_mul_f32 v[22:23], v[22:23], v[46:47] op_sel_hi:[1,0]
	v_pk_mul_f32 v[36:37], v[36:37], v[46:47] op_sel_hi:[1,0]
	v_pk_mul_f32 v[52:53], v[34:35], v[46:47] op_sel_hi:[1,0]
	v_pk_mul_f32 v[40:41], v[40:41], v[46:47] op_sel_hi:[1,0]
	v_pk_mul_f32 v[54:55], v[38:39], v[46:47] op_sel_hi:[1,0]
	v_pk_mul_f32 v[44:45], v[44:45], v[46:47] op_sel_hi:[1,0]
	v_pk_mul_f32 v[46:47], v[42:43], v[46:47] op_sel_hi:[1,0]
	v_pk_mul_f32 v[34:35], v[2:3], v[22:23]
	v_pk_mul_f32 v[32:33], v[0:1], v[32:33]
	v_pk_mul_f32 v[38:39], v[6:7], v[52:53]
	v_pk_mul_f32 v[36:37], v[4:5], v[36:37]
	v_pk_mul_f32 v[42:43], v[10:11], v[54:55]
	v_pk_mul_f32 v[40:41], v[8:9], v[40:41]
	v_pk_mul_f32 v[46:47], v[14:15], v[46:47]
	v_pk_mul_f32 v[44:45], v[12:13], v[44:45]
	global_store_dwordx4 v[20:21], v[32:35], off
	global_store_dwordx4 v[20:21], v[36:39], off offset:1024
	global_store_dwordx4 v[20:21], v[40:43], off offset:2048
	global_store_dwordx4 v[20:21], v[44:47], off offset:3072
	s_andn2_b64 exec, exec, s[6:7]
	s_cbranch_execnz .LBB0_1396
.LBB0_1397:
	s_cmp_eq_u32 s98, 1
	s_cbranch_scc1 .Lm_again
	s_cmp_eq_u32 s98, 3
	s_cbranch_scc1 .Lm_again
	s_endpgm
.Lm_again:
	s_add_u32 s98, s98, 1
	s_mov_b64 exec, -1
	s_waitcnt vmcnt(0) lgkmcnt(0)
	s_barrier
	s_mov_b64 s[0:1], s[100:101]
	v_readlane_b32 s99, v255, 63
	v_mbcnt_lo_u32_b32 v0, -1, 0
	v_mbcnt_hi_u32_b32 v0, -1, v0
	s_nop 1
	v_add_u32_e32 v0, s99, v0
	s_branch .Lp_tramp
	s_endpgm

	.amdhsa_kernel _Z10fwd_kernel4Args
		.amdhsa_group_segment_fixed_size 0
		.amdhsa_private_segment_fixed_size 0
		.amdhsa_kernarg_size 496
		.amdhsa_user_sgpr_count 2
		.amdhsa_user_sgpr_dispatch_ptr 0
		.amdhsa_user_sgpr_queue_ptr 0
		.amdhsa_user_sgpr_kernarg_segment_ptr 1
		.amdhsa_user_sgpr_dispatch_id 0
		.amdhsa_user_sgpr_kernarg_preload_length 0
		.amdhsa_user_sgpr_kernarg_preload_offset 0
		.amdhsa_user_sgpr_private_segment_size 0
		.amdhsa_uses_dynamic_stack 0
		.amdhsa_enable_private_segment 0
		.amdhsa_system_sgpr_workgroup_id_x 1
		.amdhsa_system_sgpr_workgroup_id_y 0
		.amdhsa_system_sgpr_workgroup_id_z 0
		.amdhsa_system_sgpr_workgroup_info 0
		.amdhsa_system_vgpr_workitem_id 2
		.amdhsa_next_free_vgpr 256
		.amdhsa_next_free_sgpr 102
		.amdhsa_accum_offset 256
		.amdhsa_reserve_vcc 1
		.amdhsa_float_round_mode_32 0
		.amdhsa_float_round_mode_16_64 0
		.amdhsa_float_denorm_mode_32 3
		.amdhsa_float_denorm_mode_16_64 3
		.amdhsa_dx10_clamp 1
		.amdhsa_ieee_mode 1
		.amdhsa_fp16_overflow 0
		.amdhsa_tg_split 0
		.amdhsa_exception_fp_ieee_invalid_op 0
		.amdhsa_exception_fp_denorm_src 0
		.amdhsa_exception_fp_ieee_div_zero 0
		.amdhsa_exception_fp_ieee_overflow 0
		.amdhsa_exception_fp_ieee_underflow 0
		.amdhsa_exception_fp_ieee_inexact 0
		.amdhsa_exception_int_div_zero 0
	.end_amdhsa_kernel

amdhsa.kernels:
  - .agpr_count:     0
    .args:
      - .offset:         0
        .size:           240
        .value_kind:     by_value
      - .offset:         240
        .size:           4
        .value_kind:     hidden_block_count_x
      - .offset:         244
        .size:           4
        .value_kind:     hidden_block_count_y
      - .offset:         248
        .size:           4
        .value_kind:     hidden_block_count_z
      - .offset:         252
        .size:           2
        .value_kind:     hidden_group_size_x
      - .offset:         254
        .size:           2
        .value_kind:     hidden_group_size_y
      - .offset:         256
        .size:           2
        .value_kind:     hidden_group_size_z
      - .offset:         258
        .size:           2
        .value_kind:     hidden_remainder_x
      - .offset:         260
        .size:           2
        .value_kind:     hidden_remainder_y
      - .offset:         262
        .size:           2
        .value_kind:     hidden_remainder_z
      - .offset:         280
        .size:           8
        .value_kind:     hidden_global_offset_x
      - .offset:         288
        .size:           8
        .value_kind:     hidden_global_offset_y
      - .offset:         296
        .size:           8
        .value_kind:     hidden_global_offset_z
      - .offset:         304
        .size:           2
        .value_kind:     hidden_grid_dims
      - .offset:         328
        .size:           8
        .value_kind:     hidden_multigrid_sync_arg
      - .offset:         360
        .size:           4
        .value_kind:     hidden_dynamic_lds_size
    .group_segment_fixed_size: 0
    .kernarg_segment_align: 8
    .kernarg_segment_size: 496
    .language:       OpenCL C
    .language_version:
      - 2
      - 0
    .max_flat_workgroup_size: 512
    .name:           _Z10fwd_kernel4Args
    .private_segment_fixed_size: 0
    .sgpr_count:     108
    .sgpr_spill_count: 76
    .symbol:         _Z10fwd_kernel4Args.kd
    .uniform_work_group_size: 1
    .uses_dynamic_stack: false
    .vgpr_count:     256
    .vgpr_spill_count: 0
    .wavefront_size: 64
